# adds branch-free interleaved softplus in sb attention
# speedup vs baseline: 1.0179x; 1.0035x over previous
; __device__ __forceinline__ void sb_item(const bf16_t* hbuf, const float* kmax2, bf16_t* mixed, LAS bf16_t* vT, int item, int lane) {
;     ...
;         for (int mt = 0; mt < 4; ++mt) {
;             z[mt] = z[mt] * 0.125f;
; #pragma unroll
;             for (int j = 0; j < 4; ++j) { const int kp = k0 + 16 * mt + 4 * q + j; const bool valid = (kp < qpos) && (kp >= 0); const float zz = z[mt][j];
;                 lk[mt][j] = valid ? -(fmaxf(zz, 0.f) + __logf(1.0f + __expf(-fabsf(zz)))) : 0.f; } }
.LBB0_195:
	v_add_u32_e32 v139, s15, v120
	s_cmp_gt_i32 s15, -1
	s_cselect_b64 s[22:23], -1, 0
	v_cmp_lt_i32_e32 vcc, v139, v138
	v_pk_mul_f32 v[118:119], v[118:119], s[4:5] op_sel_hi:[1,0]
	v_pk_mul_f32 v[116:117], v[116:117], s[4:5] op_sel_hi:[1,0]
	s_and_b64 vcc, s[22:23], vcc
	v_add_u32_e32 v140, 1, v139
	v_cmp_lt_i32_e64 s[0:1], v140, v138
	s_and_b64 s[36:37], s[22:23], s[0:1]
	v_add_u32_e32 v140, 2, v139
	v_cmp_lt_i32_e64 s[0:1], v140, v138
	s_and_b64 s[38:39], s[22:23], s[0:1]
	v_add_u32_e32 v142, 3, v139
	v_cmp_lt_i32_e64 s[0:1], v142, v138
	s_and_b64 s[0:1], s[22:23], s[0:1]
	v_add_u32_e32 v142, 16, v139
	s_cmpk_gt_i32 s15, 0xffef
	s_cselect_b64 s[22:23], -1, 0
	v_cmp_lt_i32_e64 s[40:41], v142, v138
	v_pk_mul_f32 v[114:115], v[114:115], s[4:5] op_sel_hi:[1,0]
	v_pk_mul_f32 v[112:113], v[112:113], s[4:5] op_sel_hi:[1,0]
	s_and_b64 s[40:41], s[22:23], s[40:41]
	v_add_u32_e32 v144, 17, v139
	v_cmp_lt_i32_e64 s[44:45], v144, v138
	s_and_b64 s[44:45], s[22:23], s[44:45]
	v_add_u32_e32 v144, 18, v139
	v_cmp_lt_i32_e64 s[46:47], v144, v138
	s_and_b64 s[46:47], s[22:23], s[46:47]
	v_add_u32_e32 v146, 19, v139
	v_cmp_lt_i32_e64 s[48:49], v146, v138
	s_and_b64 s[48:49], s[22:23], s[48:49]
	v_add_u32_e32 v146, 32, v139
	s_cmpk_gt_i32 s15, 0xffdf
	s_cselect_b64 s[22:23], -1, 0
	v_cmp_lt_i32_e64 s[50:51], v146, v138
	v_pk_mul_f32 v[110:111], v[110:111], s[4:5] op_sel_hi:[1,0]
	v_pk_mul_f32 v[108:109], v[108:109], s[4:5] op_sel_hi:[1,0]
	s_and_b64 s[50:51], s[22:23], s[50:51]
	v_add_u32_e32 v148, 33, v139
	v_cmp_lt_i32_e64 s[52:53], v148, v138
	s_and_b64 s[52:53], s[22:23], s[52:53]
	v_add_u32_e32 v148, 34, v139
	v_cmp_lt_i32_e64 s[54:55], v148, v138
	s_and_b64 s[54:55], s[22:23], s[54:55]
	v_add_u32_e32 v150, 35, v139
	v_cmp_lt_i32_e64 s[56:57], v150, v138
	s_and_b64 s[56:57], s[22:23], s[56:57]
	v_add_u32_e32 v150, 48, v139
	s_cmpk_gt_i32 s15, 0xffcf
	s_cselect_b64 s[22:23], -1, 0
	v_cmp_lt_i32_e64 s[58:59], v150, v138
	v_pk_mul_f32 v[106:107], v[106:107], s[4:5] op_sel_hi:[1,0]
	v_pk_mul_f32 v[104:105], v[104:105], s[4:5] op_sel_hi:[1,0]
	s_and_b64 s[58:59], s[22:23], s[58:59]
	v_add_u32_e32 v152, 49, v139
	v_cmp_lt_i32_e64 s[60:61], v152, v138
	s_and_b64 s[60:61], s[22:23], s[60:61]
	v_add_u32_e32 v152, 50, v139
	v_cmp_lt_i32_e64 s[62:63], v152, v138
	s_and_b64 s[62:63], s[22:23], s[62:63]
	v_add_u32_e32 v139, 51, v139
	v_cmp_lt_i32_e64 s[64:65], v139, v138
	s_and_b64 s[64:65], s[22:23], s[64:65]
	v_mul_f32_e64 v125, |v116|, s18
	v_mul_f32_e64 v123, |v117|, s18
	v_mul_f32_e64 v141, |v118|, s18
	v_mul_f32_e64 v140, |v119|, s18
	v_mul_f32_e64 v143, |v112|, s18
	v_mul_f32_e64 v142, |v113|, s18
	v_mul_f32_e64 v145, |v114|, s18
	v_mul_f32_e64 v144, |v115|, s18
	v_max_f32_e32 v192, v116, v116
	v_max_f32_e32 v194, v117, v117
	v_max_f32_e32 v196, v118, v118
	v_max_f32_e32 v198, v119, v119
	v_max_f32_e32 v200, v112, v112
	v_max_f32_e32 v202, v113, v113
	v_max_f32_e32 v204, v114, v114
	v_max_f32_e32 v212, v115, v115
	v_exp_f32_e32 v125, v125
	v_exp_f32_e32 v123, v123
	v_exp_f32_e32 v141, v141
	v_exp_f32_e32 v140, v140
	v_exp_f32_e32 v143, v143
	v_exp_f32_e32 v142, v142
	v_exp_f32_e32 v145, v145
	v_exp_f32_e32 v144, v144
	v_max_f32_e32 v192, 0, v192
	v_max_f32_e32 v194, 0, v194
	v_max_f32_e32 v196, 0, v196
	v_max_f32_e32 v198, 0, v198
	v_max_f32_e32 v200, 0, v200
	v_max_f32_e32 v202, 0, v202
	v_max_f32_e32 v204, 0, v204
	v_max_f32_e32 v212, 0, v212
	v_add_f32_e32 v125, 1.0, v125
	v_add_f32_e32 v123, 1.0, v123
	v_add_f32_e32 v141, 1.0, v141
	v_add_f32_e32 v140, 1.0, v140
	v_add_f32_e32 v143, 1.0, v143
	v_add_f32_e32 v142, 1.0, v142
	v_add_f32_e32 v145, 1.0, v145
	v_add_f32_e32 v144, 1.0, v144
	v_log_f32_e32 v125, v125
	v_log_f32_e32 v123, v123
	v_log_f32_e32 v141, v141
	v_log_f32_e32 v140, v140
	v_log_f32_e32 v143, v143
	v_log_f32_e32 v142, v142
	v_log_f32_e32 v145, v145
	v_log_f32_e32 v144, v144
	v_mul_f32_e32 v193, 0x3f317217, v125
	v_mul_f32_e32 v195, 0x3f317217, v123
	v_mul_f32_e32 v197, 0x3f317217, v141
	v_mul_f32_e32 v199, 0x3f317217, v140
	v_mul_f32_e32 v201, 0x3f317217, v143
	v_mul_f32_e32 v203, 0x3f317217, v142
	v_mul_f32_e32 v205, 0x3f317217, v145
	v_mul_f32_e32 v213, 0x3f317217, v144
	v_fma_f32 v193, v125, s19, -v193
	v_fma_f32 v195, v123, s19, -v195
	v_fma_f32 v197, v141, s19, -v197
	v_fma_f32 v199, v140, s19, -v199
	v_fma_f32 v201, v143, s19, -v201
	v_fma_f32 v203, v142, s19, -v203
	v_fma_f32 v205, v145, s19, -v205
	v_fma_f32 v213, v144, s19, -v213
	v_fmac_f32_e32 v193, 0x3377d1cf, v125
	v_fmac_f32_e32 v195, 0x3377d1cf, v123
	v_fmac_f32_e32 v197, 0x3377d1cf, v141
	v_fmac_f32_e32 v199, 0x3377d1cf, v140
	v_fmac_f32_e32 v201, 0x3377d1cf, v143
	v_fmac_f32_e32 v203, 0x3377d1cf, v142
	v_fmac_f32_e32 v205, 0x3377d1cf, v145
	v_fmac_f32_e32 v213, 0x3377d1cf, v144
	v_fmac_f32_e32 v193, 0x3f317217, v125
	v_fmac_f32_e32 v195, 0x3f317217, v123
	v_fmac_f32_e32 v197, 0x3f317217, v141
	v_fmac_f32_e32 v199, 0x3f317217, v140
	v_fmac_f32_e32 v201, 0x3f317217, v143
	v_fmac_f32_e32 v203, 0x3f317217, v142
	v_fmac_f32_e32 v205, 0x3f317217, v145
	v_fmac_f32_e32 v213, 0x3f317217, v144
	v_add_f32_e32 v125, v192, v193
	v_add_f32_e32 v123, v194, v195
	v_add_f32_e32 v141, v196, v197
	v_add_f32_e32 v140, v198, v199
	v_add_f32_e32 v143, v200, v201
	v_add_f32_e32 v142, v202, v203
	v_add_f32_e32 v145, v204, v205
	v_add_f32_e32 v144, v212, v213
	v_xor_b32_e32 v125, 0x80000000, v125
	v_xor_b32_e32 v123, 0x80000000, v123
	v_xor_b32_e32 v141, 0x80000000, v141
	v_xor_b32_e32 v140, 0x80000000, v140
	v_xor_b32_e32 v143, 0x80000000, v143
	v_xor_b32_e32 v142, 0x80000000, v142
	v_xor_b32_e32 v145, 0x80000000, v145
	v_xor_b32_e32 v144, 0x80000000, v144
	v_cndmask_b32_e32 v125, 0, v125, vcc
; __device__ __forceinline__ float bflo(unsigned u) { return __uint_as_float(u << 16); }
; __device__ __forceinline__ float bfhi(unsigned u) { return __uint_as_float(u & 0xffff0000u); }
; __device__ __forceinline__ bf16x8 pack_tiles(const f32x4& t0, const f32x4& t1) { u32x4 w; w.x = pk2(t0[0], t0[1]); w.y = pk2(t0[2], t0[3]); w.z = pk2(t1[0], t1[1]); w.w = pk2(t1[2], t1[3]); return as_bf16x8(w); }
; __device__ __forceinline__ void sb_item(const bf16_t* hbuf, const float* kmax2, bf16_t* mixed, LAS bf16_t* vT, int item, int lane) {
;     ...
;             for (int j = 0; j < 4; ++j) { const int kp = k0 + 16 * mt + 4 * q + j; const bool valid = (kp < qpos) && (kp >= 0); const float zz = z[mt][j];
;                 lk[mt][j] = valid ? -(fmaxf(zz, 0.f) + __logf(1.0f + __expf(-fabsf(zz)))) : 0.f; } }
;         bf16x8 lh[2], ll[2];
; #pragma unroll
;         for (int mb = 0; mb < 2; ++mb) { lh[mb] = pack_tiles(lk[2 * mb], lk[2 * mb + 1]);
;             const u32x4 hw = __builtin_bit_cast(u32x4, lh[mb]); f32x4 d0, d1;
;             d0[0] = lk[2 * mb][0] - bflo(hw.x); d0[1] = lk[2 * mb][1] - bfhi(hw.x); d0[2] = lk[2 * mb][2] - bflo(hw.y); d0[3] = lk[2 * mb][3] - bfhi(hw.y);
;             d1[0] = lk[2 * mb + 1][0] - bflo(hw.z); d1[1] = lk[2 * mb + 1][1] - bfhi(hw.z); d1[2] = lk[2 * mb + 1][2] - bflo(hw.w); d1[3] = lk[2 * mb + 1][3] - bfhi(hw.w);
;             ll[mb] = pack_tiles(d0, d1); }
;         f32x4 rs[4];
; #pragma unroll
;         for (int mt = 0; mt < 4; ++mt) { f32x4 acc = {0.f, 0.f, 0.f, 0.f};
; #pragma unroll
;             for (int mb = 0; mb < 2; ++mb) {
;                 const int m = 16 * mt + r; unsigned tw[4];
; #pragma unroll
;                 for (int p = 0; p < 4; ++p) { const int i0 = 2 * p, i1 = 2 * p + 1;
;                     const int ma = 32 * mb + (i0 < 4 ? 4 * q + i0 : 16 + 4 * q + i0 - 4), mbb = 32 * mb + (i1 < 4 ? 4 * q + i1 : 16 + 4 * q + i1 - 4);
;                     tw[p] = (ma >= m ? 0x3f80u : 0u) | (mbb >= m ? 0x3f800000u : 0u); }
;                 const bf16x8 tri = as_bf16x8((u32x4){tw[0], tw[1], tw[2], tw[3]});
;                 acc = __builtin_amdgcn_mfma_f32_16x16x32_bf16(tri, lh[mb], acc, 0, 0, 0);
;                 acc = __builtin_amdgcn_mfma_f32_16x16x32_bf16(tri, ll[mb], acc, 0, 0, 0); }
	v_cndmask_b32_e64 v123, 0, v123, s[36:37]
	v_cndmask_b32_e64 v141, 0, v141, s[38:39]
	v_cndmask_b32_e64 v140, 0, v140, s[0:1]
	v_cndmask_b32_e64 v143, 0, v143, s[40:41]
	v_cndmask_b32_e64 v142, 0, v142, s[44:45]
	v_cndmask_b32_e64 v145, 0, v145, s[46:47]
	v_cndmask_b32_e64 v144, 0, v144, s[48:49]
	v_mul_f32_e64 v147, |v108|, s18
	v_mul_f32_e64 v146, |v109|, s18
	v_mul_f32_e64 v149, |v110|, s18
	v_mul_f32_e64 v148, |v111|, s18
	v_mul_f32_e64 v151, |v104|, s18
	v_mul_f32_e64 v150, |v105|, s18
	v_mul_f32_e64 v153, |v106|, s18
	v_mul_f32_e64 v152, |v107|, s18
	v_max_f32_e32 v192, v108, v108
	v_max_f32_e32 v194, v109, v109
	v_max_f32_e32 v196, v110, v110
	v_max_f32_e32 v198, v111, v111
	v_max_f32_e32 v200, v104, v104
	v_max_f32_e32 v202, v105, v105
	v_max_f32_e32 v204, v106, v106
	v_max_f32_e32 v212, v107, v107
	v_exp_f32_e32 v147, v147
	v_exp_f32_e32 v146, v146
	v_exp_f32_e32 v149, v149
	v_exp_f32_e32 v148, v148
	v_exp_f32_e32 v151, v151
	v_exp_f32_e32 v150, v150
	v_exp_f32_e32 v153, v153
	v_exp_f32_e32 v152, v152
	v_max_f32_e32 v192, 0, v192
	v_max_f32_e32 v194, 0, v194
	v_max_f32_e32 v196, 0, v196
	v_max_f32_e32 v198, 0, v198
	v_max_f32_e32 v200, 0, v200
	v_max_f32_e32 v202, 0, v202
	v_max_f32_e32 v204, 0, v204
	v_max_f32_e32 v212, 0, v212
	v_add_f32_e32 v147, 1.0, v147
	v_add_f32_e32 v146, 1.0, v146
	v_add_f32_e32 v149, 1.0, v149
	v_add_f32_e32 v148, 1.0, v148
	v_add_f32_e32 v151, 1.0, v151
	v_add_f32_e32 v150, 1.0, v150
	v_add_f32_e32 v153, 1.0, v153
	v_add_f32_e32 v152, 1.0, v152
	v_log_f32_e32 v147, v147
	v_log_f32_e32 v146, v146
	v_log_f32_e32 v149, v149
	v_log_f32_e32 v148, v148
	v_log_f32_e32 v151, v151
	v_log_f32_e32 v150, v150
	v_log_f32_e32 v153, v153
	v_log_f32_e32 v152, v152
	v_mul_f32_e32 v193, 0x3f317217, v147
	v_mul_f32_e32 v195, 0x3f317217, v146
	v_mul_f32_e32 v197, 0x3f317217, v149
	v_mul_f32_e32 v199, 0x3f317217, v148
	v_mul_f32_e32 v201, 0x3f317217, v151
	v_mul_f32_e32 v203, 0x3f317217, v150
	v_mul_f32_e32 v205, 0x3f317217, v153
	v_mul_f32_e32 v213, 0x3f317217, v152
	v_fma_f32 v193, v147, s19, -v193
	v_fma_f32 v195, v146, s19, -v195
	v_fma_f32 v197, v149, s19, -v197
	v_fma_f32 v199, v148, s19, -v199
	v_fma_f32 v201, v151, s19, -v201
	v_fma_f32 v203, v150, s19, -v203
	v_fma_f32 v205, v153, s19, -v205
	v_fma_f32 v213, v152, s19, -v213
	v_fmac_f32_e32 v193, 0x3377d1cf, v147
	v_fmac_f32_e32 v195, 0x3377d1cf, v146
	v_fmac_f32_e32 v197, 0x3377d1cf, v149
	v_fmac_f32_e32 v199, 0x3377d1cf, v148
	v_fmac_f32_e32 v201, 0x3377d1cf, v151
	v_fmac_f32_e32 v203, 0x3377d1cf, v150
	v_fmac_f32_e32 v205, 0x3377d1cf, v153
	v_fmac_f32_e32 v213, 0x3377d1cf, v152
	v_fmac_f32_e32 v193, 0x3f317217, v147
	v_fmac_f32_e32 v195, 0x3f317217, v146
	v_fmac_f32_e32 v197, 0x3f317217, v149
	v_fmac_f32_e32 v199, 0x3f317217, v148
	v_fmac_f32_e32 v201, 0x3f317217, v151
	v_fmac_f32_e32 v203, 0x3f317217, v150
	v_fmac_f32_e32 v205, 0x3f317217, v153
	v_fmac_f32_e32 v213, 0x3f317217, v152
	v_add_f32_e32 v147, v192, v193
	v_add_f32_e32 v146, v194, v195
	v_add_f32_e32 v149, v196, v197
	v_add_f32_e32 v148, v198, v199
	v_add_f32_e32 v151, v200, v201
	v_add_f32_e32 v150, v202, v203
	v_add_f32_e32 v153, v204, v205
	v_add_f32_e32 v152, v212, v213
	v_xor_b32_e32 v147, 0x80000000, v147
	v_xor_b32_e32 v146, 0x80000000, v146
	v_xor_b32_e32 v149, 0x80000000, v149
	v_xor_b32_e32 v148, 0x80000000, v148
	v_xor_b32_e32 v151, 0x80000000, v151
	v_xor_b32_e32 v150, 0x80000000, v150
	v_xor_b32_e32 v153, 0x80000000, v153
	v_xor_b32_e32 v152, 0x80000000, v152
	v_cndmask_b32_e64 v147, 0, v147, s[50:51]
	v_cndmask_b32_e64 v146, 0, v146, s[52:53]
	v_cndmask_b32_e64 v149, 0, v149, s[54:55]
	v_cndmask_b32_e64 v148, 0, v148, s[56:57]
	v_cndmask_b32_e64 v151, 0, v151, s[58:59]
	v_cndmask_b32_e64 v150, 0, v150, s[60:61]
	v_cndmask_b32_e64 v153, 0, v153, s[62:63]
	v_cndmask_b32_e64 v152, 0, v152, s[64:65]
	v_cvt_pk_bf16_f32 v154, v125, v123
	v_cvt_pk_bf16_f32 v155, v141, v140
	v_cvt_pk_bf16_f32 v156, v143, v142
	v_cvt_pk_bf16_f32 v157, v145, v144
	v_cvt_pk_bf16_f32 v159, v149, v148
	v_cvt_pk_bf16_f32 v160, v151, v150
	s_nop 0
	v_lshlrev_b32_e32 v139, 16, v154
	v_sub_f32_e32 v125, v125, v139
	v_and_b32_e32 v139, 0xffff0000, v154
	v_sub_f32_e32 v123, v123, v139
	v_lshlrev_b32_e32 v139, 16, v155
	v_sub_f32_e32 v139, v141, v139
	v_and_b32_e32 v141, 0xffff0000, v155
	v_sub_f32_e32 v141, v140, v141
	v_lshlrev_b32_e32 v140, 16, v156
	v_sub_f32_e32 v143, v143, v140
	v_and_b32_e32 v140, 0xffff0000, v156
	v_sub_f32_e32 v142, v142, v140
	v_lshlrev_b32_e32 v140, 16, v157
	v_sub_f32_e32 v145, v145, v140
	v_and_b32_e32 v140, 0xffff0000, v157
	v_sub_f32_e32 v144, v144, v140
	v_cvt_pk_bf16_f32 v142, v143, v142
	v_cvt_pk_bf16_f32 v143, v145, v144
	v_and_b32_e32 v144, 0xffff0000, v159
	v_sub_f32_e32 v162, v148, v144
	v_lshlrev_b32_e32 v144, 16, v160
	v_sub_f32_e32 v163, v151, v144
	v_and_b32_e32 v144, 0xffff0000, v160
	v_cvt_pk_bf16_f32 v140, v125, v123
	v_cvt_pk_bf16_f32 v158, v147, v146
	v_cvt_pk_bf16_f32 v161, v153, v152
	v_sub_f32_e32 v164, v150, v144
	v_lshlrev_b32_e32 v123, 16, v158
	v_and_b32_e32 v125, 0xffff0000, v158
	v_lshlrev_b32_e32 v144, 16, v161
	v_sub_f32_e32 v123, v147, v123
	v_sub_f32_e32 v125, v146, v125
	v_sub_f32_e32 v153, v153, v144
	v_mfma_f32_16x16x32_bf16 v[144:147], v[36:39], v[154:157], 0
	v_cvt_pk_bf16_f32 v141, v139, v141
	v_lshlrev_b32_e32 v139, 16, v159
	s_mov_b32 s94, s92
	v_mfma_f32_16x16x32_bf16 v[176:179], v[0:3], v[154:157], 0
	s_mov_b32 s95, s92
	v_sub_f32_e32 v139, v149, v139
	s_mov_b32 s93, s92
	v_mov_b64_e32 v[150:151], s[94:95]
	v_mov_b64_e32 v[148:149], s[92:93]
	v_mfma_f32_16x16x32_bf16 v[144:147], v[36:39], v[140:143], v[144:147]
	v_and_b32_e32 v165, 0xffff0000, v161
	v_sub_f32_e32 v152, v152, v165
	v_cvt_pk_bf16_f32 v172, v123, v125
	v_mfma_f32_16x16x32_bf16 v[176:179], v[0:3], v[140:143], v[176:179]
	v_cvt_pk_bf16_f32 v173, v139, v162
	v_cvt_pk_bf16_f32 v174, v163, v164
	v_cvt_pk_bf16_f32 v175, v153, v152
	v_mfma_f32_16x16x32_bf16 v[144:147], v[148:151], v[158:161], v[144:147]
	s_waitcnt lgkmcnt(0)
; __device__ __forceinline__ float sl(float v, int src) { return __builtin_bit_cast(float, __builtin_amdgcn_ds_bpermute(src << 2, __builtin_bit_cast(int, v))); }
; __device__ __forceinline__ void lds_fence() { asm volatile("s_waitcnt lgkmcnt(0)" ::: "memory"); }
; __device__ __forceinline__ bf16x8 pack_tiles(const f32x4& t0, const f32x4& t1) { u32x4 w; w.x = pk2(t0[0], t0[1]); w.y = pk2(t0[2], t0[3]); w.z = pk2(t1[0], t1[1]); w.w = pk2(t1[2], t1[3]); return as_bf16x8(w); }
; __device__ __forceinline__ void sb_item(const bf16_t* hbuf, const float* kmax2, bf16_t* mixed, LAS bf16_t* vT, int item, int lane) {
;     ...
;         for (int mt = 0; mt < 4; ++mt) { f32x4 acc = {0.f, 0.f, 0.f, 0.f};
; #pragma unroll
;             for (int mb = 0; mb < 2; ++mb) {
;                 const int m = 16 * mt + r; unsigned tw[4];
; #pragma unroll
;                 for (int p = 0; p < 4; ++p) { const int i0 = 2 * p, i1 = 2 * p + 1;
;                     const int ma = 32 * mb + (i0 < 4 ? 4 * q + i0 : 16 + 4 * q + i0 - 4), mbb = 32 * mb + (i1 < 4 ? 4 * q + i1 : 16 + 4 * q + i1 - 4);
;                     tw[p] = (ma >= m ? 0x3f80u : 0u) | (mbb >= m ? 0x3f800000u : 0u); }
;                 const bf16x8 tri = as_bf16x8((u32x4){tw[0], tw[1], tw[2], tw[3]});
;                 acc = __builtin_amdgcn_mfma_f32_16x16x32_bf16(tri, lh[mb], acc, 0, 0, 0);
;                 acc = __builtin_amdgcn_mfma_f32_16x16x32_bf16(tri, ll[mb], acc, 0, 0, 0); }
;             rs[mt] = acc; }
;         const float total = sl(rs[0][0], r);
;         bf16x8 af[2];
;         { f32x4 av[4];
; #pragma unroll
;           for (int mt = 0; mt < 4; ++mt)
; #pragma unroll
;               for (int j = 0; j < 4; ++j) { const int kp = k0 + 16 * mt + 4 * q + j; const bool valid = (kp < qpos) && (kp >= 0); av[mt][j] = valid ? __expf(z[mt][j] + rs[mt][j] + carry) : 0.f; }
;           af[0] = pack_tiles(av[0], av[1]); af[1] = pack_tiles(av[2], av[3]); }
;         lds_fence();
; #pragma unroll
;         for (int et = 0; et < 4; ++et)
; #pragma unroll
;             for (int mb = 0; mb < 2; ++mb) O[et] = __builtin_amdgcn_mfma_f32_16x16x32_bf16(vt_frag<TLDA>(vT, et, mb, r, q), af[mb], O[et], 0, 0, 0);
;         carry += total;
;         lds_fence();
;         if (__all(carry + bound < -105.f)) break;
	s_mov_b64 s[22:23], -1
	v_mfma_f32_16x16x32_bf16 v[176:179], v[148:151], v[158:161], v[176:179]
	v_mfma_f32_16x16x32_bf16 v[144:147], v[148:151], v[172:175], v[144:147]
	v_mfma_f32_16x16x32_bf16 v[148:151], v[148:151], v[172:175], v[176:179]
	s_nop 5
	v_mov_b64_e32 v[178:179], s[30:31]
	v_mov_b64_e32 v[176:177], s[28:29]
	v_add_f32_e32 v112, v112, v148
	v_add_f32_e32 v113, v113, v149
	v_mfma_f32_16x16x32_bf16 v[152:155], v[176:179], v[154:157], 0
	v_add_f32_e32 v114, v114, v150
	v_add_f32_e32 v112, v32, v112
	v_add_f32_e32 v113, v32, v113
	v_mfma_f32_16x16x32_bf16 v[140:143], v[176:179], v[140:143], v[152:155]
	v_add_f32_e32 v114, v32, v114
	v_add_f32_e32 v115, v115, v151
	v_mul_f32_e32 v112, 0x3fb8aa3b, v112
	v_mfma_f32_16x16x32_bf16 v[152:155], v[36:39], v[158:161], v[140:143]
	v_mul_f32_e32 v113, 0x3fb8aa3b, v113
	v_mul_f32_e32 v114, 0x3fb8aa3b, v114
	v_add_f32_e32 v115, v32, v115
	v_mfma_f32_16x16x32_bf16 v[140:143], v[4:7], v[158:161], v[140:143]
	v_exp_f32_e32 v112, v112
	v_exp_f32_e32 v113, v113
	v_exp_f32_e32 v114, v114
	v_mfma_f32_16x16x32_bf16 v[140:143], v[4:7], v[172:175], v[140:143]
	v_mul_f32_e32 v115, 0x3fb8aa3b, v115
	v_exp_f32_e32 v115, v115
	v_add_f32_e32 v116, v116, v144
	v_mfma_f32_16x16x32_bf16 v[152:155], v[36:39], v[172:175], v[152:155]
	v_add_f32_e32 v117, v117, v145
	s_nop 2
	v_add_f32_e32 v104, v104, v140
	v_add_f32_e32 v105, v105, v141
	v_add_f32_e32 v106, v106, v142
	v_add_f32_e32 v107, v107, v143
	v_add_f32_e32 v104, v32, v104
	v_add_f32_e32 v105, v32, v105
	v_add_f32_e32 v106, v32, v106
	v_add_f32_e32 v107, v32, v107
	v_mul_f32_e32 v104, 0x3fb8aa3b, v104
	v_mul_f32_e32 v105, 0x3fb8aa3b, v105
	v_mul_f32_e32 v106, 0x3fb8aa3b, v106
	v_mul_f32_e32 v107, 0x3fb8aa3b, v107
	v_exp_f32_e32 v104, v104
	v_exp_f32_e32 v105, v105
	v_exp_f32_e32 v106, v106
	v_exp_f32_e32 v107, v107
	v_add_f32_e32 v110, v110, v154
	v_add_f32_e32 v111, v111, v155
	v_add_f32_e32 v110, v32, v110
	v_add_f32_e32 v111, v32, v111
	v_mul_f32_e32 v110, 0x3fb8aa3b, v110
	v_mul_f32_e32 v111, 0x3fb8aa3b, v111
	v_exp_f32_e32 v110, v110
	v_exp_f32_e32 v111, v111
	v_cndmask_b32_e64 v148, 0, v104, s[58:59]
	v_cndmask_b32_e64 v149, 0, v105, s[60:61]
	v_cndmask_b32_e64 v150, 0, v106, s[62:63]
	v_cndmask_b32_e64 v151, 0, v107, s[64:65]
	ds_read2_b64 v[104:107], v135 offset1:4
	v_add_f32_e32 v118, v118, v146
	v_add_f32_e32 v119, v119, v147
	v_add_f32_e32 v108, v108, v152
	v_add_f32_e32 v109, v109, v153
	v_add_f32_e32 v116, v32, v116
	v_add_f32_e32 v117, v32, v117
	v_add_f32_e32 v118, v32, v118
	v_add_f32_e32 v119, v32, v119
	v_cndmask_b32_e64 v112, 0, v112, s[40:41]
	v_cndmask_b32_e64 v113, 0, v113, s[44:45]
	v_cndmask_b32_e64 v123, 0, v114, s[46:47]
	v_add_f32_e32 v108, v32, v108
	v_add_f32_e32 v109, v32, v109
	v_mul_f32_e32 v116, 0x3fb8aa3b, v116
	v_mul_f32_e32 v117, 0x3fb8aa3b, v117
	v_mul_f32_e32 v118, 0x3fb8aa3b, v118
	v_mul_f32_e32 v119, 0x3fb8aa3b, v119
	v_cndmask_b32_e64 v125, 0, v115, s[48:49]
	v_mul_f32_e32 v108, 0x3fb8aa3b, v108
	v_mul_f32_e32 v109, 0x3fb8aa3b, v109
	v_cndmask_b32_e64 v146, 0, v110, s[54:55]
	v_cndmask_b32_e64 v147, 0, v111, s[56:57]
	v_cvt_pk_bf16_f32 v110, v112, v113
	ds_read2_b64 v[112:115], v135 offset0:8 offset1:12
	v_cvt_pk_bf16_f32 v111, v123, v125
	v_add_u32_e32 v123, 0x800, v135
	v_exp_f32_e32 v116, v116
	v_exp_f32_e32 v117, v117
	v_exp_f32_e32 v118, v118
	v_exp_f32_e32 v119, v119
	v_exp_f32_e32 v108, v108
	v_exp_f32_e32 v109, v109
	ds_read2_b64 v[140:143], v123 offset0:16 offset1:20
	v_cndmask_b32_e32 v116, 0, v116, vcc
	v_cndmask_b32_e64 v117, 0, v117, s[36:37]
	v_cndmask_b32_e64 v118, 0, v118, s[38:39]
	v_cndmask_b32_e64 v119, 0, v119, s[0:1]
	v_cndmask_b32_e64 v139, 0, v108, s[50:51]
	v_cndmask_b32_e64 v145, 0, v109, s[52:53]
	v_cvt_pk_bf16_f32 v108, v116, v117
	v_cvt_pk_bf16_f32 v109, v118, v119
	v_cvt_pk_bf16_f32 v116, v139, v145
	v_cvt_pk_bf16_f32 v117, v146, v147
	v_cvt_pk_bf16_f32 v118, v148, v149
	v_cvt_pk_bf16_f32 v119, v150, v151
	s_mov_b64 s[0:1], -1
	s_waitcnt lgkmcnt(2)
	v_mfma_f32_16x16x32_bf16 v[88:91], v[104:107], v[108:111], v[88:91]
	ds_read2_b64 v[104:107], v123 offset0:24 offset1:28
	v_add_u32_e32 v123, 0x1000, v135
	s_waitcnt lgkmcnt(2)
	v_mfma_f32_16x16x32_bf16 v[88:91], v[112:115], v[116:119], v[88:91]
	ds_read2_b64 v[112:115], v123 offset0:32 offset1:36
	s_waitcnt lgkmcnt(2)
	v_mfma_f32_16x16x32_bf16 v[100:103], v[140:143], v[108:111], v[100:103]
	s_waitcnt lgkmcnt(1)
	v_mfma_f32_16x16x32_bf16 v[100:103], v[104:107], v[116:119], v[100:103]
	ds_read2_b64 v[104:107], v123 offset0:40 offset1:44
	s_waitcnt lgkmcnt(1)
	v_mfma_f32_16x16x32_bf16 v[96:99], v[112:115], v[108:111], v[96:99]
	ds_read2_b64 v[112:115], v136 offset1:4
	s_waitcnt lgkmcnt(1)
	v_mfma_f32_16x16x32_bf16 v[96:99], v[104:107], v[116:119], v[96:99]
	ds_read2_b64 v[104:107], v136 offset0:8 offset1:12
	s_waitcnt lgkmcnt(0)
	s_waitcnt lgkmcnt(1)
	v_mfma_f32_16x16x32_bf16 v[92:95], v[112:115], v[108:111], v[92:95]
	ds_bpermute_b32 v108, v134, v144
	s_waitcnt lgkmcnt(0)
	v_add_f32_e32 v32, v32, v108
	v_mfma_f32_16x16x32_bf16 v[92:95], v[104:107], v[116:119], v[92:95]
	v_add_f32_e32 v104, v137, v32
	v_cmp_gt_f32_e32 vcc, s35, v104
	s_cmp_lg_u64 vcc, exec
	s_cbranch_scc0 .LBB0_192
	s_sub_i32 s15, s15, 64
	s_mov_b64 s[0:1], 0
	s_mov_b64 s[22:23], s[20:21]
	s_branch .LBB0_192

; __device__ __forceinline__ void sb_item(const bf16_t* hbuf, const float* kmax2, bf16_t* mixed, LAS bf16_t* vT, int item, int lane) {
;     ...
;         for (int mt = 0; mt < 4; ++mt) {
;             z[mt] = z[mt] * 0.125f;
; #pragma unroll
;             for (int j = 0; j < 4; ++j) { const int kp = k0 + 16 * mt + 4 * q + j; const bool valid = (kp < qpos) && (kp >= 0); const float zz = z[mt][j];
;                 lk[mt][j] = valid ? -(fmaxf(zz, 0.f) + __logf(1.0f + __expf(-fabsf(zz)))) : 0.f; } }
.LBB0_238:
	v_add_u32_e32 v157, s17, v120
	s_cmp_gt_i32 s17, -1
	s_cselect_b64 s[22:23], -1, 0
	v_cmp_lt_i32_e32 vcc, v157, v155
	v_pk_mul_f32 v[118:119], v[118:119], s[4:5] op_sel_hi:[1,0]
	v_pk_mul_f32 v[116:117], v[116:117], s[4:5] op_sel_hi:[1,0]
	s_and_b64 vcc, s[22:23], vcc
	v_add_u32_e32 v158, 1, v157
	v_cmp_lt_i32_e64 s[0:1], v158, v155
	s_and_b64 s[36:37], s[22:23], s[0:1]
	v_add_u32_e32 v158, 2, v157
	v_cmp_lt_i32_e64 s[0:1], v158, v155
	s_and_b64 s[38:39], s[22:23], s[0:1]
	v_add_u32_e32 v160, 3, v157
	v_cmp_lt_i32_e64 s[0:1], v160, v155
	s_and_b64 s[0:1], s[22:23], s[0:1]
	v_add_u32_e32 v160, 16, v157
	s_cmpk_gt_i32 s17, 0xffef
	s_cselect_b64 s[22:23], -1, 0
	v_cmp_lt_i32_e64 s[40:41], v160, v155
	v_pk_mul_f32 v[114:115], v[114:115], s[4:5] op_sel_hi:[1,0]
	v_pk_mul_f32 v[112:113], v[112:113], s[4:5] op_sel_hi:[1,0]
	s_and_b64 s[40:41], s[22:23], s[40:41]
	v_add_u32_e32 v162, 17, v157
	v_cmp_lt_i32_e64 s[44:45], v162, v155
	s_and_b64 s[44:45], s[22:23], s[44:45]
	v_add_u32_e32 v162, 18, v157
	v_cmp_lt_i32_e64 s[46:47], v162, v155
	s_and_b64 s[46:47], s[22:23], s[46:47]
	v_add_u32_e32 v164, 19, v157
	v_cmp_lt_i32_e64 s[48:49], v164, v155
	s_and_b64 s[48:49], s[22:23], s[48:49]
	v_add_u32_e32 v164, 32, v157
	s_cmpk_gt_i32 s17, 0xffdf
	s_cselect_b64 s[22:23], -1, 0
	v_cmp_lt_i32_e64 s[50:51], v164, v155
	v_pk_mul_f32 v[110:111], v[110:111], s[4:5] op_sel_hi:[1,0]
	v_pk_mul_f32 v[108:109], v[108:109], s[4:5] op_sel_hi:[1,0]
	s_and_b64 s[50:51], s[22:23], s[50:51]
	v_add_u32_e32 v164, 33, v157
	v_cmp_lt_i32_e64 s[52:53], v164, v155
	s_and_b64 s[52:53], s[22:23], s[52:53]
	v_add_u32_e32 v164, 34, v157
	v_cmp_lt_i32_e64 s[54:55], v164, v155
	s_and_b64 s[54:55], s[22:23], s[54:55]
	v_add_u32_e32 v164, 35, v157
	v_cmp_lt_i32_e64 s[56:57], v164, v155
	s_and_b64 s[56:57], s[22:23], s[56:57]
	v_add_u32_e32 v164, 48, v157
	s_cmpk_gt_i32 s17, 0xffcf
	s_cselect_b64 s[22:23], -1, 0
	v_cmp_lt_i32_e64 s[58:59], v164, v155
	v_pk_mul_f32 v[106:107], v[106:107], s[4:5] op_sel_hi:[1,0]
	v_pk_mul_f32 v[104:105], v[104:105], s[4:5] op_sel_hi:[1,0]
	s_and_b64 s[58:59], s[22:23], s[58:59]
	v_add_u32_e32 v164, 49, v157
	v_cmp_lt_i32_e64 s[60:61], v164, v155
	s_and_b64 s[60:61], s[22:23], s[60:61]
	v_add_u32_e32 v164, 50, v157
	v_cmp_lt_i32_e64 s[62:63], v164, v155
	s_and_b64 s[62:63], s[22:23], s[62:63]
	v_add_u32_e32 v157, 51, v157
	v_cmp_lt_i32_e64 s[64:65], v157, v155
	s_and_b64 s[64:65], s[22:23], s[64:65]
	v_mul_f32_e64 v156, |v116|, s18
	v_mul_f32_e64 v32, |v117|, s18
	v_mul_f32_e64 v159, |v118|, s18
	v_mul_f32_e64 v158, |v119|, s18
	v_mul_f32_e64 v161, |v112|, s18
	v_mul_f32_e64 v160, |v113|, s18
	v_mul_f32_e64 v163, |v114|, s18
	v_mul_f32_e64 v162, |v115|, s18
	v_max_f32_e32 v192, v116, v116
	v_max_f32_e32 v194, v117, v117
	v_max_f32_e32 v196, v118, v118
	v_max_f32_e32 v198, v119, v119
	v_max_f32_e32 v200, v112, v112
	v_max_f32_e32 v202, v113, v113
	v_max_f32_e32 v204, v114, v114
	v_max_f32_e32 v212, v115, v115
	v_exp_f32_e32 v156, v156
	v_exp_f32_e32 v32, v32
	v_exp_f32_e32 v159, v159
	v_exp_f32_e32 v158, v158
	v_exp_f32_e32 v161, v161
	v_exp_f32_e32 v160, v160
	v_exp_f32_e32 v163, v163
	v_exp_f32_e32 v162, v162
	v_max_f32_e32 v192, 0, v192
	v_max_f32_e32 v194, 0, v194
	v_max_f32_e32 v196, 0, v196
	v_max_f32_e32 v198, 0, v198
	v_max_f32_e32 v200, 0, v200
	v_max_f32_e32 v202, 0, v202
	v_max_f32_e32 v204, 0, v204
	v_max_f32_e32 v212, 0, v212
	v_add_f32_e32 v156, 1.0, v156
	v_add_f32_e32 v32, 1.0, v32
	v_add_f32_e32 v159, 1.0, v159
	v_add_f32_e32 v158, 1.0, v158
	v_add_f32_e32 v161, 1.0, v161
	v_add_f32_e32 v160, 1.0, v160
	v_add_f32_e32 v163, 1.0, v163
	v_add_f32_e32 v162, 1.0, v162
	v_log_f32_e32 v156, v156
	v_log_f32_e32 v32, v32
	v_log_f32_e32 v159, v159
	v_log_f32_e32 v158, v158
	v_log_f32_e32 v161, v161
	v_log_f32_e32 v160, v160
	v_log_f32_e32 v163, v163
	v_log_f32_e32 v162, v162
	v_mul_f32_e32 v193, 0x3f317217, v156
	v_mul_f32_e32 v195, 0x3f317217, v32
	v_mul_f32_e32 v197, 0x3f317217, v159
	v_mul_f32_e32 v199, 0x3f317217, v158
	v_mul_f32_e32 v201, 0x3f317217, v161
	v_mul_f32_e32 v203, 0x3f317217, v160
	v_mul_f32_e32 v205, 0x3f317217, v163
	v_mul_f32_e32 v213, 0x3f317217, v162
	v_fma_f32 v193, v156, s19, -v193
	v_fma_f32 v195, v32, s19, -v195
	v_fma_f32 v197, v159, s19, -v197
	v_fma_f32 v199, v158, s19, -v199
	v_fma_f32 v201, v161, s19, -v201
	v_fma_f32 v203, v160, s19, -v203
	v_fma_f32 v205, v163, s19, -v205
	v_fma_f32 v213, v162, s19, -v213
	v_fmac_f32_e32 v193, 0x3377d1cf, v156
	v_fmac_f32_e32 v195, 0x3377d1cf, v32
	v_fmac_f32_e32 v197, 0x3377d1cf, v159
	v_fmac_f32_e32 v199, 0x3377d1cf, v158
	v_fmac_f32_e32 v201, 0x3377d1cf, v161
	v_fmac_f32_e32 v203, 0x3377d1cf, v160
	v_fmac_f32_e32 v205, 0x3377d1cf, v163
	v_fmac_f32_e32 v213, 0x3377d1cf, v162
	v_fmac_f32_e32 v193, 0x3f317217, v156
	v_fmac_f32_e32 v195, 0x3f317217, v32
	v_fmac_f32_e32 v197, 0x3f317217, v159
	v_fmac_f32_e32 v199, 0x3f317217, v158
	v_fmac_f32_e32 v201, 0x3f317217, v161
	v_fmac_f32_e32 v203, 0x3f317217, v160
	v_fmac_f32_e32 v205, 0x3f317217, v163
	v_fmac_f32_e32 v213, 0x3f317217, v162
	v_add_f32_e32 v156, v192, v193
	v_add_f32_e32 v32, v194, v195
	v_add_f32_e32 v159, v196, v197
	v_add_f32_e32 v158, v198, v199
	v_add_f32_e32 v161, v200, v201
	v_add_f32_e32 v160, v202, v203
	v_add_f32_e32 v163, v204, v205
	v_add_f32_e32 v162, v212, v213
	v_xor_b32_e32 v156, 0x80000000, v156
	v_xor_b32_e32 v32, 0x80000000, v32
	v_xor_b32_e32 v159, 0x80000000, v159
	v_xor_b32_e32 v158, 0x80000000, v158
	v_xor_b32_e32 v161, 0x80000000, v161
	v_xor_b32_e32 v160, 0x80000000, v160
	v_xor_b32_e32 v163, 0x80000000, v163
	v_xor_b32_e32 v162, 0x80000000, v162
	v_cndmask_b32_e32 v156, 0, v156, vcc
; __device__ __forceinline__ float bflo(unsigned u) { return __uint_as_float(u << 16); }
; __device__ __forceinline__ float bfhi(unsigned u) { return __uint_as_float(u & 0xffff0000u); }
; __device__ __forceinline__ bf16x8 pack_tiles(const f32x4& t0, const f32x4& t1) { u32x4 w; w.x = pk2(t0[0], t0[1]); w.y = pk2(t0[2], t0[3]); w.z = pk2(t1[0], t1[1]); w.w = pk2(t1[2], t1[3]); return as_bf16x8(w); }
; __device__ __forceinline__ void sb_item(const bf16_t* hbuf, const float* kmax2, bf16_t* mixed, LAS bf16_t* vT, int item, int lane) {
;     ...
;             for (int j = 0; j < 4; ++j) { const int kp = k0 + 16 * mt + 4 * q + j; const bool valid = (kp < qpos) && (kp >= 0); const float zz = z[mt][j];
;                 lk[mt][j] = valid ? -(fmaxf(zz, 0.f) + __logf(1.0f + __expf(-fabsf(zz)))) : 0.f; } }
;         bf16x8 lh[2], ll[2];
; #pragma unroll
;         for (int mb = 0; mb < 2; ++mb) { lh[mb] = pack_tiles(lk[2 * mb], lk[2 * mb + 1]);
;             const u32x4 hw = __builtin_bit_cast(u32x4, lh[mb]); f32x4 d0, d1;
;             d0[0] = lk[2 * mb][0] - bflo(hw.x); d0[1] = lk[2 * mb][1] - bfhi(hw.x); d0[2] = lk[2 * mb][2] - bflo(hw.y); d0[3] = lk[2 * mb][3] - bfhi(hw.y);
;             d1[0] = lk[2 * mb + 1][0] - bflo(hw.z); d1[1] = lk[2 * mb + 1][1] - bfhi(hw.z); d1[2] = lk[2 * mb + 1][2] - bflo(hw.w); d1[3] = lk[2 * mb + 1][3] - bfhi(hw.w);
;             ll[mb] = pack_tiles(d0, d1); }
;         f32x4 rs[4];
; #pragma unroll
;         for (int mt = 0; mt < 4; ++mt) { f32x4 acc = {0.f, 0.f, 0.f, 0.f};
; #pragma unroll
;             for (int mb = 0; mb < 2; ++mb) {
;                 const int m = 16 * mt + r; unsigned tw[4];
; #pragma unroll
;                 for (int p = 0; p < 4; ++p) { const int i0 = 2 * p, i1 = 2 * p + 1;
;                     const int ma = 32 * mb + (i0 < 4 ? 4 * q + i0 : 16 + 4 * q + i0 - 4), mbb = 32 * mb + (i1 < 4 ? 4 * q + i1 : 16 + 4 * q + i1 - 4);
;                     tw[p] = (ma >= m ? 0x3f80u : 0u) | (mbb >= m ? 0x3f800000u : 0u); }
;                 const bf16x8 tri = as_bf16x8((u32x4){tw[0], tw[1], tw[2], tw[3]});
;                 acc = __builtin_amdgcn_mfma_f32_16x16x32_bf16(tri, lh[mb], acc, 0, 0, 0);
;                 acc = __builtin_amdgcn_mfma_f32_16x16x32_bf16(tri, ll[mb], acc, 0, 0, 0); }
	v_cndmask_b32_e64 v32, 0, v32, s[36:37]
	v_cndmask_b32_e64 v159, 0, v159, s[38:39]
	v_cndmask_b32_e64 v158, 0, v158, s[0:1]
	v_cndmask_b32_e64 v161, 0, v161, s[40:41]
	v_cndmask_b32_e64 v160, 0, v160, s[44:45]
	v_cndmask_b32_e64 v163, 0, v163, s[46:47]
	v_cndmask_b32_e64 v162, 0, v162, s[48:49]
	v_mul_f32_e64 v172, |v108|, s18
	v_mul_f32_e64 v169, |v109|, s18
	v_mul_f32_e64 v174, |v110|, s18
	v_mul_f32_e64 v173, |v111|, s18
	v_mul_f32_e64 v176, |v104|, s18
	v_mul_f32_e64 v175, |v105|, s18
	v_mul_f32_e64 v178, |v106|, s18
	v_mul_f32_e64 v177, |v107|, s18
	v_max_f32_e32 v192, v108, v108
	v_max_f32_e32 v194, v109, v109
	v_max_f32_e32 v196, v110, v110
	v_max_f32_e32 v198, v111, v111
	v_max_f32_e32 v200, v104, v104
	v_max_f32_e32 v202, v105, v105
	v_max_f32_e32 v204, v106, v106
	v_max_f32_e32 v212, v107, v107
	v_exp_f32_e32 v172, v172
	v_exp_f32_e32 v169, v169
	v_exp_f32_e32 v174, v174
	v_exp_f32_e32 v173, v173
	v_exp_f32_e32 v176, v176
	v_exp_f32_e32 v175, v175
	v_exp_f32_e32 v178, v178
	v_exp_f32_e32 v177, v177
	v_max_f32_e32 v192, 0, v192
	v_max_f32_e32 v194, 0, v194
	v_max_f32_e32 v196, 0, v196
	v_max_f32_e32 v198, 0, v198
	v_max_f32_e32 v200, 0, v200
	v_max_f32_e32 v202, 0, v202
	v_max_f32_e32 v204, 0, v204
	v_max_f32_e32 v212, 0, v212
	v_add_f32_e32 v172, 1.0, v172
	v_add_f32_e32 v169, 1.0, v169
	v_add_f32_e32 v174, 1.0, v174
	v_add_f32_e32 v173, 1.0, v173
	v_add_f32_e32 v176, 1.0, v176
	v_add_f32_e32 v175, 1.0, v175
	v_add_f32_e32 v178, 1.0, v178
	v_add_f32_e32 v177, 1.0, v177
	v_log_f32_e32 v172, v172
	v_log_f32_e32 v169, v169
	v_log_f32_e32 v174, v174
	v_log_f32_e32 v173, v173
	v_log_f32_e32 v176, v176
	v_log_f32_e32 v175, v175
	v_log_f32_e32 v178, v178
	v_log_f32_e32 v177, v177
	v_mul_f32_e32 v193, 0x3f317217, v172
	v_mul_f32_e32 v195, 0x3f317217, v169
	v_mul_f32_e32 v197, 0x3f317217, v174
	v_mul_f32_e32 v199, 0x3f317217, v173
	v_mul_f32_e32 v201, 0x3f317217, v176
	v_mul_f32_e32 v203, 0x3f317217, v175
	v_mul_f32_e32 v205, 0x3f317217, v178
	v_mul_f32_e32 v213, 0x3f317217, v177
	v_fma_f32 v193, v172, s19, -v193
	v_fma_f32 v195, v169, s19, -v195
	v_fma_f32 v197, v174, s19, -v197
	v_fma_f32 v199, v173, s19, -v199
	v_fma_f32 v201, v176, s19, -v201
	v_fma_f32 v203, v175, s19, -v203
	v_fma_f32 v205, v178, s19, -v205
	v_fma_f32 v213, v177, s19, -v213
	v_fmac_f32_e32 v193, 0x3377d1cf, v172
	v_fmac_f32_e32 v195, 0x3377d1cf, v169
	v_fmac_f32_e32 v197, 0x3377d1cf, v174
	v_fmac_f32_e32 v199, 0x3377d1cf, v173
	v_fmac_f32_e32 v201, 0x3377d1cf, v176
	v_fmac_f32_e32 v203, 0x3377d1cf, v175
	v_fmac_f32_e32 v205, 0x3377d1cf, v178
	v_fmac_f32_e32 v213, 0x3377d1cf, v177
	v_fmac_f32_e32 v193, 0x3f317217, v172
	v_fmac_f32_e32 v195, 0x3f317217, v169
	v_fmac_f32_e32 v197, 0x3f317217, v174
	v_fmac_f32_e32 v199, 0x3f317217, v173
	v_fmac_f32_e32 v201, 0x3f317217, v176
	v_fmac_f32_e32 v203, 0x3f317217, v175
	v_fmac_f32_e32 v205, 0x3f317217, v178
	v_fmac_f32_e32 v213, 0x3f317217, v177
	v_add_f32_e32 v172, v192, v193
	v_add_f32_e32 v169, v194, v195
	v_add_f32_e32 v174, v196, v197
	v_add_f32_e32 v173, v198, v199
	v_add_f32_e32 v176, v200, v201
	v_add_f32_e32 v175, v202, v203
	v_add_f32_e32 v178, v204, v205
	v_add_f32_e32 v177, v212, v213
	v_xor_b32_e32 v172, 0x80000000, v172
	v_xor_b32_e32 v169, 0x80000000, v169
	v_xor_b32_e32 v174, 0x80000000, v174
	v_xor_b32_e32 v173, 0x80000000, v173
	v_xor_b32_e32 v176, 0x80000000, v176
	v_xor_b32_e32 v175, 0x80000000, v175
	v_xor_b32_e32 v178, 0x80000000, v178
	v_xor_b32_e32 v177, 0x80000000, v177
	v_cndmask_b32_e64 v172, 0, v172, s[50:51]
	v_cndmask_b32_e64 v169, 0, v169, s[52:53]
	v_cndmask_b32_e64 v174, 0, v174, s[54:55]
	v_cndmask_b32_e64 v173, 0, v173, s[56:57]
	v_cndmask_b32_e64 v176, 0, v176, s[58:59]
	v_cndmask_b32_e64 v175, 0, v175, s[60:61]
	v_cndmask_b32_e64 v178, 0, v178, s[62:63]
	v_cndmask_b32_e64 v177, 0, v177, s[64:65]
	v_cvt_pk_bf16_f32 v180, v156, v32
	v_cvt_pk_bf16_f32 v181, v159, v158
	v_cvt_pk_bf16_f32 v182, v161, v160
	v_cvt_pk_bf16_f32 v183, v163, v162
	s_mov_b32 s94, s92
	v_lshlrev_b32_e32 v157, 16, v180
	v_sub_f32_e32 v156, v156, v157
	v_and_b32_e32 v157, 0xffff0000, v180
	v_sub_f32_e32 v32, v32, v157
	v_lshlrev_b32_e32 v157, 16, v181
	v_sub_f32_e32 v157, v159, v157
	v_and_b32_e32 v159, 0xffff0000, v181
	v_sub_f32_e32 v158, v158, v159
	v_lshlrev_b32_e32 v159, 16, v182
	v_sub_f32_e32 v159, v161, v159
	v_and_b32_e32 v161, 0xffff0000, v182
	v_sub_f32_e32 v160, v160, v161
	v_lshlrev_b32_e32 v161, 16, v183
	v_sub_f32_e32 v161, v163, v161
	v_and_b32_e32 v163, 0xffff0000, v183
	v_sub_f32_e32 v162, v162, v163
	v_cvt_pk_bf16_f32 v156, v156, v32
	v_cvt_pk_bf16_f32 v157, v157, v158
	v_cvt_pk_bf16_f32 v158, v159, v160
	v_cvt_pk_bf16_f32 v160, v172, v169
	v_cvt_pk_bf16_f32 v159, v161, v162
	v_cvt_pk_bf16_f32 v162, v176, v175
	v_cvt_pk_bf16_f32 v163, v178, v177
	v_cvt_pk_bf16_f32 v161, v174, v173
	s_mov_b32 s95, s92
	v_lshlrev_b32_e32 v32, 16, v160
	v_sub_f32_e32 v32, v172, v32
	v_lshlrev_b32_e32 v172, 16, v162
	v_sub_f32_e32 v179, v176, v172
	v_and_b32_e32 v172, 0xffff0000, v162
	v_and_b32_e32 v164, 0xffff0000, v160
	v_sub_f32_e32 v188, v175, v172
	v_lshlrev_b32_e32 v172, 16, v163
	v_and_b32_e32 v176, 0xffff0000, v163
	v_sub_f32_e32 v164, v169, v164
	v_lshlrev_b32_e32 v165, 16, v161
	v_and_b32_e32 v169, 0xffff0000, v161
	v_sub_f32_e32 v189, v178, v172
	v_sub_f32_e32 v190, v177, v176
	v_sub_f32_e32 v165, v174, v165
	v_sub_f32_e32 v169, v173, v169
	v_mfma_f32_16x16x32_bf16 v[172:175], v[36:39], v[180:183], 0
	v_cvt_pk_bf16_f32 v178, v179, v188
	v_cvt_pk_bf16_f32 v179, v189, v190
	s_mov_b32 s93, s92
	v_mfma_f32_16x16x32_bf16 v[188:191], v[0:3], v[180:183], 0
	v_mov_b64_e32 v[186:187], s[94:95]
	v_mov_b64_e32 v[184:185], s[92:93]
	v_cvt_pk_bf16_f32 v176, v32, v164
	v_mfma_f32_16x16x32_bf16 v[172:175], v[36:39], v[156:159], v[172:175]
	v_cvt_pk_bf16_f32 v177, v165, v169
	s_waitcnt lgkmcnt(0)
; __device__ __forceinline__ float sl(float v, int src) { return __builtin_bit_cast(float, __builtin_amdgcn_ds_bpermute(src << 2, __builtin_bit_cast(int, v))); }
; __device__ __forceinline__ void lds_fence() { asm volatile("s_waitcnt lgkmcnt(0)" ::: "memory"); }
; __device__ __forceinline__ bf16x8 pack_tiles(const f32x4& t0, const f32x4& t1) { u32x4 w; w.x = pk2(t0[0], t0[1]); w.y = pk2(t0[2], t0[3]); w.z = pk2(t1[0], t1[1]); w.w = pk2(t1[2], t1[3]); return as_bf16x8(w); }
; __device__ __forceinline__ void sb_item(const bf16_t* hbuf, const float* kmax2, bf16_t* mixed, LAS bf16_t* vT, int item, int lane) {
;     ...
;         for (int mt = 0; mt < 4; ++mt) { f32x4 acc = {0.f, 0.f, 0.f, 0.f};
; #pragma unroll
;             for (int mb = 0; mb < 2; ++mb) {
;                 const int m = 16 * mt + r; unsigned tw[4];
; #pragma unroll
;                 for (int p = 0; p < 4; ++p) { const int i0 = 2 * p, i1 = 2 * p + 1;
;                     const int ma = 32 * mb + (i0 < 4 ? 4 * q + i0 : 16 + 4 * q + i0 - 4), mbb = 32 * mb + (i1 < 4 ? 4 * q + i1 : 16 + 4 * q + i1 - 4);
;                     tw[p] = (ma >= m ? 0x3f80u : 0u) | (mbb >= m ? 0x3f800000u : 0u); }
;                 const bf16x8 tri = as_bf16x8((u32x4){tw[0], tw[1], tw[2], tw[3]});
;                 acc = __builtin_amdgcn_mfma_f32_16x16x32_bf16(tri, lh[mb], acc, 0, 0, 0);
;                 acc = __builtin_amdgcn_mfma_f32_16x16x32_bf16(tri, ll[mb], acc, 0, 0, 0); }
;             rs[mt] = acc; }
;         const float total = sl(rs[0][0], r);
;         bf16x8 af[2];
;         { f32x4 av[4];
; #pragma unroll
;           for (int mt = 0; mt < 4; ++mt)
; #pragma unroll
;               for (int j = 0; j < 4; ++j) { const int kp = k0 + 16 * mt + 4 * q + j; const bool valid = (kp < qpos) && (kp >= 0); av[mt][j] = valid ? __expf(z[mt][j] + rs[mt][j] + carry) : 0.f; }
;           af[0] = pack_tiles(av[0], av[1]); af[1] = pack_tiles(av[2], av[3]); }
;         lds_fence();
; #pragma unroll
;         for (int et = 0; et < 4; ++et)
; #pragma unroll
;             for (int mb = 0; mb < 2; ++mb) O[et] = __builtin_amdgcn_mfma_f32_16x16x32_bf16(vt_frag<TLDA>(vT, et, mb, r, q), af[mb], O[et], 0, 0, 0);
;         carry += total;
;         lds_fence();
;         if (__all(carry + bound < -105.f)) break;
	s_mov_b64 s[22:23], -1
	v_mfma_f32_16x16x32_bf16 v[188:191], v[0:3], v[156:159], v[188:191]
	v_mfma_f32_16x16x32_bf16 v[172:175], v[184:187], v[160:163], v[172:175]
	v_mfma_f32_16x16x32_bf16 v[188:191], v[184:187], v[160:163], v[188:191]
	v_mfma_f32_16x16x32_bf16 v[172:175], v[184:187], v[176:179], v[172:175]
	v_mfma_f32_16x16x32_bf16 v[184:187], v[184:187], v[176:179], v[188:191]
	s_nop 5
	v_mov_b64_e32 v[190:191], s[30:31]
	v_mov_b64_e32 v[188:189], s[28:29]
	v_add_f32_e32 v112, v112, v184
	v_add_f32_e32 v113, v113, v185
	v_mfma_f32_16x16x32_bf16 v[180:183], v[188:191], v[180:183], 0
	v_add_f32_e32 v112, v153, v112
	v_add_f32_e32 v113, v153, v113
	v_mul_f32_e32 v112, 0x3fb8aa3b, v112
	v_mfma_f32_16x16x32_bf16 v[156:159], v[188:191], v[156:159], v[180:183]
	v_mul_f32_e32 v113, 0x3fb8aa3b, v113
	v_exp_f32_e32 v112, v112
	v_exp_f32_e32 v113, v113
	v_mfma_f32_16x16x32_bf16 v[180:183], v[36:39], v[160:163], v[156:159]
	v_add_f32_e32 v32, v116, v172
	v_add_f32_e32 v116, v117, v173
	v_add_f32_e32 v117, v118, v174
	v_mfma_f32_16x16x32_bf16 v[180:183], v[36:39], v[176:179], v[180:183]
	v_add_f32_e32 v118, v119, v175
	v_cndmask_b32_e64 v119, 0, v112, s[40:41]
	v_add_f32_e32 v112, v114, v186
	v_mfma_f32_16x16x32_bf16 v[156:159], v[4:7], v[160:163], v[156:159]
	v_cndmask_b32_e64 v160, 0, v113, s[44:45]
	s_nop 2
	v_add_f32_e32 v108, v108, v180
	v_add_f32_e32 v108, v153, v108
	v_mfma_f32_16x16x32_bf16 v[156:159], v[4:7], v[176:179], v[156:159]
	v_mul_f32_e32 v108, 0x3fb8aa3b, v108
	v_exp_f32_e32 v108, v108
	v_add_f32_e32 v109, v109, v181
	v_add_f32_e32 v109, v153, v109
	v_mul_f32_e32 v109, 0x3fb8aa3b, v109
	s_nop 2
	v_add_f32_e32 v104, v104, v156
	v_add_f32_e32 v104, v153, v104
	v_exp_f32_e32 v109, v109
	v_mul_f32_e32 v104, 0x3fb8aa3b, v104
	v_cndmask_b32_e64 v163, 0, v108, s[50:51]
	v_add_f32_e32 v108, v110, v182
	v_exp_f32_e32 v104, v104
	v_add_f32_e32 v108, v153, v108
	v_mul_f32_e32 v108, 0x3fb8aa3b, v108
	v_cndmask_b32_e64 v164, 0, v109, s[52:53]
	v_exp_f32_e32 v108, v108
	v_add_f32_e32 v109, v111, v183
	v_add_f32_e32 v105, v105, v157
	v_add_f32_e32 v109, v153, v109
	v_add_f32_e32 v105, v153, v105
	v_cndmask_b32_e64 v165, 0, v104, s[58:59]
	v_add_f32_e32 v104, v106, v158
	v_mul_f32_e32 v109, 0x3fb8aa3b, v109
	v_mul_f32_e32 v105, 0x3fb8aa3b, v105
	v_add_f32_e32 v104, v153, v104
	v_exp_f32_e32 v109, v109
	v_exp_f32_e32 v105, v105
	v_mul_f32_e32 v104, 0x3fb8aa3b, v104
	v_add_f32_e32 v113, v115, v187
	v_cndmask_b32_e64 v156, 0, v108, s[54:55]
	v_exp_f32_e32 v108, v104
	v_add_f32_e32 v104, v107, v159
	v_add_f32_e32 v112, v153, v112
	v_add_f32_e32 v113, v153, v113
	v_add_f32_e32 v104, v153, v104
	v_mul_f32_e32 v112, 0x3fb8aa3b, v112
	v_mul_f32_e32 v113, 0x3fb8aa3b, v113
	v_mul_f32_e32 v104, 0x3fb8aa3b, v104
	v_add_u32_e32 v158, v152, v148
	v_exp_f32_e32 v112, v112
	v_exp_f32_e32 v113, v113
	v_cndmask_b32_e64 v157, 0, v109, s[56:57]
	v_cndmask_b32_e64 v169, 0, v105, s[60:61]
	v_exp_f32_e32 v109, v104
	ds_read2_b64 v[104:107], v158 offset1:4
	v_add_f32_e32 v32, v153, v32
	v_add_f32_e32 v116, v153, v116
	v_add_f32_e32 v117, v153, v117
	v_add_f32_e32 v118, v153, v118
	v_mul_f32_e32 v32, 0x3fb8aa3b, v32
	v_mul_f32_e32 v116, 0x3fb8aa3b, v116
	v_mul_f32_e32 v117, 0x3fb8aa3b, v117
	v_mul_f32_e32 v118, 0x3fb8aa3b, v118
	v_cndmask_b32_e64 v161, 0, v112, s[46:47]
	v_cndmask_b32_e64 v162, 0, v113, s[48:49]
	ds_read2_b64 v[112:115], v158 offset0:8 offset1:12
	v_exp_f32_e32 v32, v32
	v_exp_f32_e32 v116, v116
	v_exp_f32_e32 v117, v117
	v_exp_f32_e32 v118, v118
	v_cndmask_b32_e32 v32, 0, v32, vcc
	v_cndmask_b32_e64 v116, 0, v116, s[36:37]
	v_cndmask_b32_e64 v117, 0, v117, s[38:39]
	v_cndmask_b32_e64 v118, 0, v118, s[0:1]
	v_cndmask_b32_e64 v159, 0, v108, s[62:63]
	v_cndmask_b32_e64 v173, 0, v109, s[64:65]
	v_cvt_pk_bf16_f32 v108, v32, v116
	v_cvt_pk_bf16_f32 v109, v117, v118
	v_cvt_pk_bf16_f32 v110, v119, v160
	v_cvt_pk_bf16_f32 v111, v161, v162
	v_add_u32_e32 v32, 0x800, v158
	s_waitcnt lgkmcnt(1)
	v_mfma_f32_16x16x32_bf16 v[100:103], v[104:107], v[108:111], v[100:103]
	v_cvt_pk_bf16_f32 v116, v163, v164
	v_cvt_pk_bf16_f32 v117, v156, v157
	v_cvt_pk_bf16_f32 v118, v165, v169
	v_cvt_pk_bf16_f32 v119, v159, v173
	s_mov_b64 s[0:1], -1
	s_waitcnt lgkmcnt(0)
	v_mfma_f32_16x16x32_bf16 v[100:103], v[112:115], v[116:119], v[100:103]
	ds_read2_b64 v[104:107], v32 offset0:16 offset1:20
	ds_read2_b64 v[112:115], v32 offset0:24 offset1:28
	v_add_u32_e32 v32, 0x1000, v158
	s_waitcnt lgkmcnt(1)
	v_mfma_f32_16x16x32_bf16 v[96:99], v[104:107], v[108:111], v[96:99]
	ds_read2_b64 v[104:107], v32 offset0:32 offset1:36
	s_waitcnt lgkmcnt(1)
	v_mfma_f32_16x16x32_bf16 v[96:99], v[112:115], v[116:119], v[96:99]
	ds_read2_b64 v[112:115], v32 offset0:40 offset1:44
	v_add_u32_e32 v32, v152, v150
	s_waitcnt lgkmcnt(1)
	v_mfma_f32_16x16x32_bf16 v[92:95], v[104:107], v[108:111], v[92:95]
	ds_read2_b64 v[104:107], v32 offset1:4
	s_waitcnt lgkmcnt(1)
	v_mfma_f32_16x16x32_bf16 v[92:95], v[112:115], v[116:119], v[92:95]
	ds_read2_b64 v[112:115], v32 offset0:8 offset1:12
	ds_bpermute_b32 v32, v135, v172
	s_waitcnt lgkmcnt(0)
	s_waitcnt lgkmcnt(2)
	v_mfma_f32_16x16x32_bf16 v[88:91], v[104:107], v[108:111], v[88:91]
	s_waitcnt lgkmcnt(0)
	v_add_f32_e32 v153, v153, v32
	v_add_f32_e32 v32, v154, v153
	v_cmp_gt_f32_e32 vcc, s35, v32
	v_mfma_f32_16x16x32_bf16 v[88:91], v[112:115], v[116:119], v[88:91]
	s_cmp_lg_u64 vcc, exec
	s_cbranch_scc0 .LBB0_235
	s_sub_i32 s17, s17, 64
	s_mov_b64 s[0:1], 0
	s_mov_b64 s[22:23], s[20:21]
	s_branch .LBB0_235

; __device__ __forceinline__ void sb_item(const bf16_t* hbuf, const float* kmax2, bf16_t* mixed, LAS bf16_t* vT, int item, int lane) {
;     ...
;         for (int mt = 0; mt < 4; ++mt) {
;             z[mt] = z[mt] * 0.125f;
; #pragma unroll
;             for (int j = 0; j < 4; ++j) { const int kp = k0 + 16 * mt + 4 * q + j; const bool valid = (kp < qpos) && (kp >= 0); const float zz = z[mt][j];
;                 lk[mt][j] = valid ? -(fmaxf(zz, 0.f) + __logf(1.0f + __expf(-fabsf(zz)))) : 0.f; } }
.LBB0_287:
	v_add_u32_e32 v149, s17, v120
	s_cmp_gt_i32 s17, -1
	s_cselect_b64 s[26:27], -1, 0
	v_cmp_lt_i32_e32 vcc, v149, v144
	v_pk_mul_f32 v[114:115], v[114:115], s[4:5] op_sel_hi:[1,0]
	v_pk_mul_f32 v[112:113], v[112:113], s[4:5] op_sel_hi:[1,0]
	s_and_b64 vcc, s[26:27], vcc
	v_add_u32_e32 v147, 1, v149
	v_cmp_lt_i32_e64 s[0:1], v147, v144
	s_and_b64 s[38:39], s[26:27], s[0:1]
	v_add_u32_e32 v147, 2, v149
	v_cmp_lt_i32_e64 s[0:1], v147, v144
	s_and_b64 s[40:41], s[26:27], s[0:1]
	v_add_u32_e32 v149, 3, v149
	v_cmp_lt_i32_e64 s[0:1], v149, v144
	s_and_b64 s[0:1], s[26:27], s[0:1]
	v_add_u32_e32 v153, s17, v136
	s_cmpk_gt_i32 s17, 0xffef
	s_cselect_b64 s[26:27], -1, 0
	v_cmp_lt_i32_e64 s[44:45], v153, v144
	v_pk_mul_f32 v[110:111], v[110:111], s[4:5] op_sel_hi:[1,0]
	v_pk_mul_f32 v[108:109], v[108:109], s[4:5] op_sel_hi:[1,0]
	s_and_b64 s[44:45], s[26:27], s[44:45]
	v_add_u32_e32 v151, 1, v153
	v_cmp_lt_i32_e64 s[46:47], v151, v144
	s_and_b64 s[46:47], s[26:27], s[46:47]
	v_add_u32_e32 v151, 2, v153
	v_cmp_lt_i32_e64 s[48:49], v151, v144
	s_and_b64 s[48:49], s[26:27], s[48:49]
	v_add_u32_e32 v153, 3, v153
	v_cmp_lt_i32_e64 s[50:51], v153, v144
	s_and_b64 s[50:51], s[26:27], s[50:51]
	v_add_u32_e32 v157, s17, v137
	s_cmpk_gt_i32 s17, 0xffdf
	s_cselect_b64 s[26:27], -1, 0
	v_cmp_lt_i32_e64 s[52:53], v157, v144
	v_pk_mul_f32 v[106:107], v[106:107], s[4:5] op_sel_hi:[1,0]
	v_pk_mul_f32 v[104:105], v[104:105], s[4:5] op_sel_hi:[1,0]
	s_and_b64 s[52:53], s[26:27], s[52:53]
	v_add_u32_e32 v155, 1, v157
	v_cmp_lt_i32_e64 s[54:55], v155, v144
	s_and_b64 s[54:55], s[26:27], s[54:55]
	v_add_u32_e32 v155, 2, v157
	v_cmp_lt_i32_e64 s[56:57], v155, v144
	s_and_b64 s[56:57], s[26:27], s[56:57]
	v_add_u32_e32 v157, 3, v157
	v_cmp_lt_i32_e64 s[58:59], v157, v144
	s_and_b64 s[58:59], s[26:27], s[58:59]
	v_add_u32_e32 v161, s17, v138
	s_cmpk_gt_i32 s17, 0xffcf
	s_cselect_b64 s[26:27], -1, 0
	v_cmp_lt_i32_e64 s[60:61], v161, v144
	v_pk_mul_f32 v[102:103], v[102:103], s[4:5] op_sel_hi:[1,0]
	v_pk_mul_f32 v[100:101], v[100:101], s[4:5] op_sel_hi:[1,0]
	s_and_b64 s[60:61], s[26:27], s[60:61]
	v_add_u32_e32 v159, 1, v161
	v_cmp_lt_i32_e64 s[62:63], v159, v144
	s_and_b64 s[62:63], s[26:27], s[62:63]
	v_add_u32_e32 v159, 2, v161
	v_cmp_lt_i32_e64 s[64:65], v159, v144
	s_and_b64 s[64:65], s[26:27], s[64:65]
	v_add_u32_e32 v161, 3, v161
	v_cmp_lt_i32_e64 s[66:67], v161, v144
	s_and_b64 s[66:67], s[26:27], s[66:67]
	v_mul_f32_e64 v146, |v112|, s18
	v_mul_f32_e64 v145, |v113|, s18
	v_mul_f32_e64 v148, |v114|, s18
	v_mul_f32_e64 v147, |v115|, s18
	v_mul_f32_e64 v150, |v108|, s18
	v_mul_f32_e64 v149, |v109|, s18
	v_mul_f32_e64 v152, |v110|, s18
	v_mul_f32_e64 v151, |v111|, s18
	v_max_f32_e32 v192, v112, v112
	v_max_f32_e32 v194, v113, v113
	v_max_f32_e32 v196, v114, v114
	v_max_f32_e32 v198, v115, v115
	v_max_f32_e32 v200, v108, v108
	v_max_f32_e32 v202, v109, v109
	v_max_f32_e32 v204, v110, v110
	v_max_f32_e32 v212, v111, v111
	v_exp_f32_e32 v146, v146
	v_exp_f32_e32 v145, v145
	v_exp_f32_e32 v148, v148
	v_exp_f32_e32 v147, v147
	v_exp_f32_e32 v150, v150
	v_exp_f32_e32 v149, v149
	v_exp_f32_e32 v152, v152
	v_exp_f32_e32 v151, v151
	v_max_f32_e32 v192, 0, v192
	v_max_f32_e32 v194, 0, v194
	v_max_f32_e32 v196, 0, v196
	v_max_f32_e32 v198, 0, v198
	v_max_f32_e32 v200, 0, v200
	v_max_f32_e32 v202, 0, v202
	v_max_f32_e32 v204, 0, v204
	v_max_f32_e32 v212, 0, v212
	v_add_f32_e32 v146, 1.0, v146
	v_add_f32_e32 v145, 1.0, v145
	v_add_f32_e32 v148, 1.0, v148
	v_add_f32_e32 v147, 1.0, v147
	v_add_f32_e32 v150, 1.0, v150
	v_add_f32_e32 v149, 1.0, v149
	v_add_f32_e32 v152, 1.0, v152
	v_add_f32_e32 v151, 1.0, v151
	v_log_f32_e32 v146, v146
	v_log_f32_e32 v145, v145
	v_log_f32_e32 v148, v148
	v_log_f32_e32 v147, v147
	v_log_f32_e32 v150, v150
	v_log_f32_e32 v149, v149
	v_log_f32_e32 v152, v152
	v_log_f32_e32 v151, v151
	v_mul_f32_e32 v193, 0x3f317217, v146
	v_mul_f32_e32 v195, 0x3f317217, v145
	v_mul_f32_e32 v197, 0x3f317217, v148
	v_mul_f32_e32 v199, 0x3f317217, v147
	v_mul_f32_e32 v201, 0x3f317217, v150
	v_mul_f32_e32 v203, 0x3f317217, v149
	v_mul_f32_e32 v205, 0x3f317217, v152
	v_mul_f32_e32 v213, 0x3f317217, v151
	v_fma_f32 v193, v146, s19, -v193
	v_fma_f32 v195, v145, s19, -v195
	v_fma_f32 v197, v148, s19, -v197
	v_fma_f32 v199, v147, s19, -v199
	v_fma_f32 v201, v150, s19, -v201
	v_fma_f32 v203, v149, s19, -v203
	v_fma_f32 v205, v152, s19, -v205
	v_fma_f32 v213, v151, s19, -v213
	v_fmac_f32_e32 v193, 0x3377d1cf, v146
	v_fmac_f32_e32 v195, 0x3377d1cf, v145
	v_fmac_f32_e32 v197, 0x3377d1cf, v148
	v_fmac_f32_e32 v199, 0x3377d1cf, v147
	v_fmac_f32_e32 v201, 0x3377d1cf, v150
	v_fmac_f32_e32 v203, 0x3377d1cf, v149
	v_fmac_f32_e32 v205, 0x3377d1cf, v152
	v_fmac_f32_e32 v213, 0x3377d1cf, v151
	v_fmac_f32_e32 v193, 0x3f317217, v146
	v_fmac_f32_e32 v195, 0x3f317217, v145
	v_fmac_f32_e32 v197, 0x3f317217, v148
	v_fmac_f32_e32 v199, 0x3f317217, v147
	v_fmac_f32_e32 v201, 0x3f317217, v150
	v_fmac_f32_e32 v203, 0x3f317217, v149
	v_fmac_f32_e32 v205, 0x3f317217, v152
	v_fmac_f32_e32 v213, 0x3f317217, v151
	v_add_f32_e32 v146, v192, v193
	v_add_f32_e32 v145, v194, v195
	v_add_f32_e32 v148, v196, v197
	v_add_f32_e32 v147, v198, v199
	v_add_f32_e32 v150, v200, v201
	v_add_f32_e32 v149, v202, v203
	v_add_f32_e32 v152, v204, v205
	v_add_f32_e32 v151, v212, v213
	v_xor_b32_e32 v146, 0x80000000, v146
	v_xor_b32_e32 v145, 0x80000000, v145
	v_xor_b32_e32 v148, 0x80000000, v148
	v_xor_b32_e32 v147, 0x80000000, v147
	v_xor_b32_e32 v150, 0x80000000, v150
	v_xor_b32_e32 v149, 0x80000000, v149
	v_xor_b32_e32 v152, 0x80000000, v152
	v_xor_b32_e32 v151, 0x80000000, v151
	v_cndmask_b32_e32 v146, 0, v146, vcc
; __device__ __forceinline__ float bflo(unsigned u) { return __uint_as_float(u << 16); }
; __device__ __forceinline__ float bfhi(unsigned u) { return __uint_as_float(u & 0xffff0000u); }
; __device__ __forceinline__ bf16x8 pack_tiles(const f32x4& t0, const f32x4& t1) { u32x4 w; w.x = pk2(t0[0], t0[1]); w.y = pk2(t0[2], t0[3]); w.z = pk2(t1[0], t1[1]); w.w = pk2(t1[2], t1[3]); return as_bf16x8(w); }
; __device__ __forceinline__ void sb_item(const bf16_t* hbuf, const float* kmax2, bf16_t* mixed, LAS bf16_t* vT, int item, int lane) {
;     ...
;             for (int j = 0; j < 4; ++j) { const int kp = k0 + 16 * mt + 4 * q + j; const bool valid = (kp < qpos) && (kp >= 0); const float zz = z[mt][j];
;                 lk[mt][j] = valid ? -(fmaxf(zz, 0.f) + __logf(1.0f + __expf(-fabsf(zz)))) : 0.f; } }
;         bf16x8 lh[2], ll[2];
; #pragma unroll
;         for (int mb = 0; mb < 2; ++mb) { lh[mb] = pack_tiles(lk[2 * mb], lk[2 * mb + 1]);
;             const u32x4 hw = __builtin_bit_cast(u32x4, lh[mb]); f32x4 d0, d1;
;             d0[0] = lk[2 * mb][0] - bflo(hw.x); d0[1] = lk[2 * mb][1] - bfhi(hw.x); d0[2] = lk[2 * mb][2] - bflo(hw.y); d0[3] = lk[2 * mb][3] - bfhi(hw.y);
;             d1[0] = lk[2 * mb + 1][0] - bflo(hw.z); d1[1] = lk[2 * mb + 1][1] - bfhi(hw.z); d1[2] = lk[2 * mb + 1][2] - bflo(hw.w); d1[3] = lk[2 * mb + 1][3] - bfhi(hw.w);
;             ll[mb] = pack_tiles(d0, d1); }
;         f32x4 rs[4];
; #pragma unroll
;         for (int mt = 0; mt < 4; ++mt) { f32x4 acc = {0.f, 0.f, 0.f, 0.f};
; #pragma unroll
;             for (int mb = 0; mb < 2; ++mb) {
;                 const int m = 16 * mt + r; unsigned tw[4];
; #pragma unroll
;                 for (int p = 0; p < 4; ++p) { const int i0 = 2 * p, i1 = 2 * p + 1;
;                     const int ma = 32 * mb + (i0 < 4 ? 4 * q + i0 : 16 + 4 * q + i0 - 4), mbb = 32 * mb + (i1 < 4 ? 4 * q + i1 : 16 + 4 * q + i1 - 4);
;                     tw[p] = (ma >= m ? 0x3f80u : 0u) | (mbb >= m ? 0x3f800000u : 0u); }
;                 const bf16x8 tri = as_bf16x8((u32x4){tw[0], tw[1], tw[2], tw[3]});
;                 acc = __builtin_amdgcn_mfma_f32_16x16x32_bf16(tri, lh[mb], acc, 0, 0, 0);
;                 acc = __builtin_amdgcn_mfma_f32_16x16x32_bf16(tri, ll[mb], acc, 0, 0, 0); }
	v_cndmask_b32_e64 v145, 0, v145, s[38:39]
	v_cndmask_b32_e64 v148, 0, v148, s[40:41]
	v_cndmask_b32_e64 v147, 0, v147, s[0:1]
	v_cndmask_b32_e64 v150, 0, v150, s[44:45]
	v_cndmask_b32_e64 v149, 0, v149, s[46:47]
	v_cndmask_b32_e64 v152, 0, v152, s[48:49]
	v_cndmask_b32_e64 v151, 0, v151, s[50:51]
	v_mul_f32_e64 v154, |v104|, s18
	v_mul_f32_e64 v153, |v105|, s18
	v_mul_f32_e64 v156, |v106|, s18
	v_mul_f32_e64 v155, |v107|, s18
	v_mul_f32_e64 v158, |v100|, s18
	v_mul_f32_e64 v157, |v101|, s18
	v_mul_f32_e64 v160, |v102|, s18
	v_mul_f32_e64 v159, |v103|, s18
	v_max_f32_e32 v192, v104, v104
	v_max_f32_e32 v194, v105, v105
	v_max_f32_e32 v196, v106, v106
	v_max_f32_e32 v198, v107, v107
	v_max_f32_e32 v200, v100, v100
	v_max_f32_e32 v202, v101, v101
	v_max_f32_e32 v204, v102, v102
	v_max_f32_e32 v212, v103, v103
	v_exp_f32_e32 v154, v154
	v_exp_f32_e32 v153, v153
	v_exp_f32_e32 v156, v156
	v_exp_f32_e32 v155, v155
	v_exp_f32_e32 v158, v158
	v_exp_f32_e32 v157, v157
	v_exp_f32_e32 v160, v160
	v_exp_f32_e32 v159, v159
	v_max_f32_e32 v192, 0, v192
	v_max_f32_e32 v194, 0, v194
	v_max_f32_e32 v196, 0, v196
	v_max_f32_e32 v198, 0, v198
	v_max_f32_e32 v200, 0, v200
	v_max_f32_e32 v202, 0, v202
	v_max_f32_e32 v204, 0, v204
	v_max_f32_e32 v212, 0, v212
	v_add_f32_e32 v154, 1.0, v154
	v_add_f32_e32 v153, 1.0, v153
	v_add_f32_e32 v156, 1.0, v156
	v_add_f32_e32 v155, 1.0, v155
	v_add_f32_e32 v158, 1.0, v158
	v_add_f32_e32 v157, 1.0, v157
	v_add_f32_e32 v160, 1.0, v160
	v_add_f32_e32 v159, 1.0, v159
	v_log_f32_e32 v154, v154
	v_log_f32_e32 v153, v153
	v_log_f32_e32 v156, v156
	v_log_f32_e32 v155, v155
	v_log_f32_e32 v158, v158
	v_log_f32_e32 v157, v157
	v_log_f32_e32 v160, v160
	v_log_f32_e32 v159, v159
	v_mul_f32_e32 v193, 0x3f317217, v154
	v_mul_f32_e32 v195, 0x3f317217, v153
	v_mul_f32_e32 v197, 0x3f317217, v156
	v_mul_f32_e32 v199, 0x3f317217, v155
	v_mul_f32_e32 v201, 0x3f317217, v158
	v_mul_f32_e32 v203, 0x3f317217, v157
	v_mul_f32_e32 v205, 0x3f317217, v160
	v_mul_f32_e32 v213, 0x3f317217, v159
	v_fma_f32 v193, v154, s19, -v193
	v_fma_f32 v195, v153, s19, -v195
	v_fma_f32 v197, v156, s19, -v197
	v_fma_f32 v199, v155, s19, -v199
	v_fma_f32 v201, v158, s19, -v201
	v_fma_f32 v203, v157, s19, -v203
	v_fma_f32 v205, v160, s19, -v205
	v_fma_f32 v213, v159, s19, -v213
	v_fmac_f32_e32 v193, 0x3377d1cf, v154
	v_fmac_f32_e32 v195, 0x3377d1cf, v153
	v_fmac_f32_e32 v197, 0x3377d1cf, v156
	v_fmac_f32_e32 v199, 0x3377d1cf, v155
	v_fmac_f32_e32 v201, 0x3377d1cf, v158
	v_fmac_f32_e32 v203, 0x3377d1cf, v157
	v_fmac_f32_e32 v205, 0x3377d1cf, v160
	v_fmac_f32_e32 v213, 0x3377d1cf, v159
	v_fmac_f32_e32 v193, 0x3f317217, v154
	v_fmac_f32_e32 v195, 0x3f317217, v153
	v_fmac_f32_e32 v197, 0x3f317217, v156
	v_fmac_f32_e32 v199, 0x3f317217, v155
	v_fmac_f32_e32 v201, 0x3f317217, v158
	v_fmac_f32_e32 v203, 0x3f317217, v157
	v_fmac_f32_e32 v205, 0x3f317217, v160
	v_fmac_f32_e32 v213, 0x3f317217, v159
	v_add_f32_e32 v154, v192, v193
	v_add_f32_e32 v153, v194, v195
	v_add_f32_e32 v156, v196, v197
	v_add_f32_e32 v155, v198, v199
	v_add_f32_e32 v158, v200, v201
	v_add_f32_e32 v157, v202, v203
	v_add_f32_e32 v160, v204, v205
	v_add_f32_e32 v159, v212, v213
	v_xor_b32_e32 v154, 0x80000000, v154
	v_xor_b32_e32 v153, 0x80000000, v153
	v_xor_b32_e32 v156, 0x80000000, v156
	v_xor_b32_e32 v155, 0x80000000, v155
	v_xor_b32_e32 v158, 0x80000000, v158
	v_xor_b32_e32 v157, 0x80000000, v157
	v_xor_b32_e32 v160, 0x80000000, v160
	v_xor_b32_e32 v159, 0x80000000, v159
	v_cndmask_b32_e64 v154, 0, v154, s[52:53]
	v_cndmask_b32_e64 v153, 0, v153, s[54:55]
	v_cndmask_b32_e64 v156, 0, v156, s[56:57]
	v_cndmask_b32_e64 v155, 0, v155, s[58:59]
	v_cndmask_b32_e64 v158, 0, v158, s[60:61]
	v_cndmask_b32_e64 v157, 0, v157, s[62:63]
	v_cndmask_b32_e64 v160, 0, v160, s[64:65]
	v_cndmask_b32_e64 v159, 0, v159, s[66:67]
	v_cvt_pk_bf16_f32 v172, v146, v145
	v_cvt_pk_bf16_f32 v173, v148, v147
	v_cvt_pk_bf16_f32 v174, v150, v149
	v_cvt_pk_bf16_f32 v175, v152, v151
	v_cvt_pk_bf16_f32 v176, v154, v153
	v_cvt_pk_bf16_f32 v177, v156, v155
	s_nop 0
	v_lshlrev_b32_e32 v161, 16, v172
	v_sub_f32_e32 v146, v146, v161
	v_and_b32_e32 v161, 0xffff0000, v172
	v_sub_f32_e32 v145, v145, v161
	v_lshlrev_b32_e32 v161, 16, v173
	v_sub_f32_e32 v148, v148, v161
	v_and_b32_e32 v161, 0xffff0000, v173
	v_sub_f32_e32 v147, v147, v161
	v_lshlrev_b32_e32 v161, 16, v174
	v_sub_f32_e32 v150, v150, v161
	v_and_b32_e32 v161, 0xffff0000, v174
	v_sub_f32_e32 v149, v149, v161
	v_lshlrev_b32_e32 v161, 16, v175
	v_sub_f32_e32 v152, v152, v161
	v_and_b32_e32 v161, 0xffff0000, v175
	v_cvt_pk_bf16_f32 v147, v148, v147
	v_cvt_pk_bf16_f32 v148, v150, v149
	v_and_b32_e32 v150, 0xffff0000, v176
	v_sub_f32_e32 v151, v151, v161
	v_sub_f32_e32 v161, v153, v150
	v_lshlrev_b32_e32 v150, 16, v177
	v_sub_f32_e32 v162, v156, v150
	v_and_b32_e32 v150, 0xffff0000, v177
	v_cvt_pk_bf16_f32 v178, v158, v157
	v_sub_f32_e32 v163, v155, v150
	v_lshlrev_b32_e32 v150, 16, v178
	v_cvt_pk_bf16_f32 v179, v160, v159
	v_sub_f32_e32 v164, v158, v150
	v_and_b32_e32 v150, 0xffff0000, v178
	v_and_b32_e32 v158, 0xffff0000, v179
	v_cvt_pk_bf16_f32 v146, v146, v145
	v_lshlrev_b32_e32 v145, 16, v176
	v_sub_f32_e32 v165, v157, v150
	v_lshlrev_b32_e32 v150, 16, v179
	v_sub_f32_e32 v180, v159, v158
	v_cvt_pk_bf16_f32 v149, v152, v151
	v_sub_f32_e32 v145, v154, v145
	v_sub_f32_e32 v169, v160, v150
	v_mfma_f32_16x16x32_bf16 v[150:153], v[36:39], v[172:175], 0
	v_cvt_pk_bf16_f32 v158, v145, v161
	v_cvt_pk_bf16_f32 v161, v169, v180
	s_mov_b32 s94, s92
	v_mfma_f32_16x16x32_bf16 v[180:183], v[32:35], v[172:175], 0
	s_mov_b32 s95, s92
	s_mov_b32 s93, s92
	v_mov_b64_e32 v[156:157], s[94:95]
	v_mov_b64_e32 v[154:155], s[92:93]
	v_mfma_f32_16x16x32_bf16 v[150:153], v[36:39], v[146:149], v[150:153]
	v_cvt_pk_bf16_f32 v159, v162, v163
	v_cvt_pk_bf16_f32 v160, v164, v165
	s_waitcnt lgkmcnt(0)
; __device__ __forceinline__ float sl(float v, int src) { return __builtin_bit_cast(float, __builtin_amdgcn_ds_bpermute(src << 2, __builtin_bit_cast(int, v))); }
; __device__ __forceinline__ void lds_fence() { asm volatile("s_waitcnt lgkmcnt(0)" ::: "memory"); }
; __device__ __forceinline__ bf16x8 pack_tiles(const f32x4& t0, const f32x4& t1) { u32x4 w; w.x = pk2(t0[0], t0[1]); w.y = pk2(t0[2], t0[3]); w.z = pk2(t1[0], t1[1]); w.w = pk2(t1[2], t1[3]); return as_bf16x8(w); }
; __device__ __forceinline__ void sb_item(const bf16_t* hbuf, const float* kmax2, bf16_t* mixed, LAS bf16_t* vT, int item, int lane) {
;     ...
;         for (int mt = 0; mt < 4; ++mt) { f32x4 acc = {0.f, 0.f, 0.f, 0.f};
; #pragma unroll
;             for (int mb = 0; mb < 2; ++mb) {
;                 const int m = 16 * mt + r; unsigned tw[4];
; #pragma unroll
;                 for (int p = 0; p < 4; ++p) { const int i0 = 2 * p, i1 = 2 * p + 1;
;                     const int ma = 32 * mb + (i0 < 4 ? 4 * q + i0 : 16 + 4 * q + i0 - 4), mbb = 32 * mb + (i1 < 4 ? 4 * q + i1 : 16 + 4 * q + i1 - 4);
;                     tw[p] = (ma >= m ? 0x3f80u : 0u) | (mbb >= m ? 0x3f800000u : 0u); }
;                 const bf16x8 tri = as_bf16x8((u32x4){tw[0], tw[1], tw[2], tw[3]});
;                 acc = __builtin_amdgcn_mfma_f32_16x16x32_bf16(tri, lh[mb], acc, 0, 0, 0);
;                 acc = __builtin_amdgcn_mfma_f32_16x16x32_bf16(tri, ll[mb], acc, 0, 0, 0); }
;             rs[mt] = acc; }
;         const float total = sl(rs[0][0], r);
;         bf16x8 af[2];
;         { f32x4 av[4];
; #pragma unroll
;           for (int mt = 0; mt < 4; ++mt)
; #pragma unroll
;               for (int j = 0; j < 4; ++j) { const int kp = k0 + 16 * mt + 4 * q + j; const bool valid = (kp < qpos) && (kp >= 0); av[mt][j] = valid ? __expf(z[mt][j] + rs[mt][j] + carry) : 0.f; }
;           af[0] = pack_tiles(av[0], av[1]); af[1] = pack_tiles(av[2], av[3]); }
;         lds_fence();
; #pragma unroll
;         for (int et = 0; et < 4; ++et)
; #pragma unroll
;             for (int mb = 0; mb < 2; ++mb) O[et] = __builtin_amdgcn_mfma_f32_16x16x32_bf16(vt_frag<TLDA>(vT, et, mb, r, q), af[mb], O[et], 0, 0, 0);
;         carry += total;
;         lds_fence();
;         if (__all(carry + bound < -105.f)) break;
	v_mfma_f32_16x16x32_bf16 v[180:183], v[32:35], v[146:149], v[180:183]
	s_mov_b64 s[26:27], -1
	v_mfma_f32_16x16x32_bf16 v[150:153], v[154:157], v[176:179], v[150:153]
	v_mfma_f32_16x16x32_bf16 v[180:183], v[154:157], v[176:179], v[180:183]
	v_mfma_f32_16x16x32_bf16 v[150:153], v[154:157], v[158:161], v[150:153]
	v_mfma_f32_16x16x32_bf16 v[154:157], v[154:157], v[158:161], v[180:183]
	s_nop 5
	v_mov_b64_e32 v[182:183], s[30:31]
	v_mov_b64_e32 v[180:181], s[28:29]
	v_add_f32_e32 v108, v108, v154
	v_add_f32_e32 v109, v109, v155
	v_mfma_f32_16x16x32_bf16 v[172:175], v[180:183], v[172:175], 0
	v_add_f32_e32 v108, v142, v108
	v_add_f32_e32 v109, v142, v109
	v_mul_f32_e32 v108, 0x3fb8aa3b, v108
	v_mfma_f32_16x16x32_bf16 v[146:149], v[180:183], v[146:149], v[172:175]
	v_mul_f32_e32 v109, 0x3fb8aa3b, v109
	v_exp_f32_e32 v108, v108
	v_exp_f32_e32 v109, v109
	v_mfma_f32_16x16x32_bf16 v[172:175], v[36:39], v[176:179], v[146:149]
	v_add_f32_e32 v113, v113, v151
	v_cndmask_b32_e64 v145, 0, v108, s[44:45]
	v_cndmask_b32_e64 v151, 0, v109, s[46:47]
	v_mfma_f32_16x16x32_bf16 v[146:149], v[0:3], v[176:179], v[146:149]
	v_add_f32_e32 v108, v110, v156
	v_add_f32_e32 v109, v111, v157
	v_add_f32_e32 v108, v142, v108
	v_mfma_f32_16x16x32_bf16 v[172:175], v[36:39], v[158:161], v[172:175]
	v_add_f32_e32 v109, v142, v109
	v_mul_f32_e32 v108, 0x3fb8aa3b, v108
	v_mul_f32_e32 v109, 0x3fb8aa3b, v109
	v_mfma_f32_16x16x32_bf16 v[146:149], v[0:3], v[158:161], v[146:149]
	v_exp_f32_e32 v108, v108
	s_nop 2
	v_add_f32_e32 v104, v104, v172
	v_add_f32_e32 v104, v142, v104
	v_mul_f32_e32 v104, 0x3fb8aa3b, v104
	v_exp_f32_e32 v104, v104
	v_add_f32_e32 v100, v100, v146
	v_add_f32_e32 v100, v142, v100
	v_mul_f32_e32 v100, 0x3fb8aa3b, v100
	v_exp_f32_e32 v100, v100
	v_add_f32_e32 v101, v101, v147
	v_add_f32_e32 v101, v142, v101
	v_mul_f32_e32 v101, 0x3fb8aa3b, v101
	v_cndmask_b32_e64 v154, 0, v104, s[52:53]
	v_add_f32_e32 v104, v106, v174
	v_exp_f32_e32 v101, v101
	v_cndmask_b32_e64 v158, 0, v100, s[60:61]
	v_add_f32_e32 v100, v102, v148
	v_add_f32_e32 v104, v142, v104
	v_add_f32_e32 v100, v142, v100
	v_add_f32_e32 v105, v105, v173
	v_mul_f32_e32 v104, 0x3fb8aa3b, v104
	v_mul_f32_e32 v100, 0x3fb8aa3b, v100
	v_add_f32_e32 v105, v142, v105
	v_exp_f32_e32 v104, v104
	v_exp_f32_e32 v100, v100
	v_mul_f32_e32 v105, 0x3fb8aa3b, v105
	v_cndmask_b32_e64 v159, 0, v101, s[62:63]
	v_add_f32_e32 v101, v103, v149
	v_exp_f32_e32 v105, v105
	v_add_f32_e32 v101, v142, v101
	v_mul_f32_e32 v101, 0x3fb8aa3b, v101
	v_exp_f32_e32 v109, v109
	v_cndmask_b32_e64 v156, 0, v104, s[56:57]
	v_exp_f32_e32 v104, v101
	v_cndmask_b32_e64 v160, 0, v100, s[64:65]
	ds_read2_b64 v[100:103], v139 offset1:4
	v_add_f32_e32 v112, v112, v150
	v_add_f32_e32 v114, v114, v152
	v_add_f32_e32 v115, v115, v153
	v_cndmask_b32_e64 v155, 0, v105, s[54:55]
	v_add_f32_e32 v105, v107, v175
	v_add_f32_e32 v112, v142, v112
	v_add_f32_e32 v113, v142, v113
	v_add_f32_e32 v114, v142, v114
	v_add_f32_e32 v115, v142, v115
	v_add_f32_e32 v105, v142, v105
	v_mul_f32_e32 v112, 0x3fb8aa3b, v112
	v_mul_f32_e32 v113, 0x3fb8aa3b, v113
	v_mul_f32_e32 v114, 0x3fb8aa3b, v114
	v_mul_f32_e32 v115, 0x3fb8aa3b, v115
	v_cndmask_b32_e64 v152, 0, v108, s[48:49]
	v_cndmask_b32_e64 v153, 0, v109, s[50:51]
	v_mul_f32_e32 v105, 0x3fb8aa3b, v105
	ds_read2_b64 v[108:111], v139 offset0:8 offset1:12
	v_exp_f32_e32 v112, v112
	v_exp_f32_e32 v113, v113
	v_exp_f32_e32 v114, v114
	v_exp_f32_e32 v115, v115
	v_exp_f32_e32 v105, v105
	ds_read2_b64 v[146:149], v140 offset1:4
	v_cndmask_b32_e32 v112, 0, v112, vcc
	v_cndmask_b32_e64 v113, 0, v113, s[38:39]
	v_cndmask_b32_e64 v114, 0, v114, s[40:41]
	v_cndmask_b32_e64 v115, 0, v115, s[0:1]
	v_cndmask_b32_e64 v157, 0, v105, s[58:59]
	v_cndmask_b32_e64 v161, 0, v104, s[66:67]
	v_cvt_pk_bf16_f32 v104, v112, v113
	v_cvt_pk_bf16_f32 v105, v114, v115
	v_cvt_pk_bf16_f32 v106, v145, v151
	v_cvt_pk_bf16_f32 v107, v152, v153
	v_add_u32_e32 v145, 0x1000, v139
	s_waitcnt lgkmcnt(2)
	v_mfma_f32_16x16x32_bf16 v[48:51], v[100:103], v[104:107], v[48:51]
	ds_read2_b64 v[100:103], v140 offset0:8 offset1:12
	v_cvt_pk_bf16_f32 v112, v154, v155
	v_cvt_pk_bf16_f32 v113, v156, v157
	v_cvt_pk_bf16_f32 v114, v158, v159
	v_cvt_pk_bf16_f32 v115, v160, v161
	s_waitcnt lgkmcnt(1)
	v_mfma_f32_16x16x32_bf16 v[76:79], v[146:149], v[104:107], v[76:79]
	s_mov_b64 s[0:1], -1
	v_mfma_f32_16x16x32_bf16 v[48:51], v[108:111], v[112:115], v[48:51]
	ds_read2_b64 v[108:111], v145 offset0:32 offset1:36
	s_waitcnt lgkmcnt(1)
	v_mfma_f32_16x16x32_bf16 v[76:79], v[100:103], v[112:115], v[76:79]
	ds_read2_b64 v[100:103], v145 offset0:40 offset1:44
	s_waitcnt lgkmcnt(1)
	v_mfma_f32_16x16x32_bf16 v[64:67], v[108:111], v[104:107], v[64:67]
	ds_read2_b64 v[108:111], v141 offset1:4
	s_waitcnt lgkmcnt(1)
	v_mfma_f32_16x16x32_bf16 v[64:67], v[100:103], v[112:115], v[64:67]
	ds_read2_b64 v[100:103], v141 offset0:8 offset1:12
	s_waitcnt lgkmcnt(0)
	s_waitcnt lgkmcnt(1)
	v_mfma_f32_16x16x32_bf16 v[52:55], v[108:111], v[104:107], v[52:55]
	ds_bpermute_b32 v104, v135, v150
	s_waitcnt lgkmcnt(0)
	v_add_f32_e32 v142, v142, v104
	v_mfma_f32_16x16x32_bf16 v[52:55], v[100:103], v[112:115], v[52:55]
	v_add_f32_e32 v100, v143, v142
	v_cmp_gt_f32_e32 vcc, s35, v100
	s_cmp_lg_u64 vcc, exec
	s_cbranch_scc0 .LBB0_284
	s_sub_i32 s17, s17, 64
	s_mov_b64 s[0:1], 0
	s_mov_b64 s[26:27], s[22:23]
	s_branch .LBB0_284
